# dead SGPR-reload v_readlane removal extended to the whole kernel (1455 removed)
# speedup vs baseline: 1.0151x; 1.0073x over previous
.LBB0_20:
	s_lshl_b32 s81, s96, 3
	s_add_u32 s0, s0, 0x130
	s_nop 1
	s_addc_u32 s1, s1, 0
	s_lshl_b32 s3, s96, 1
	v_readlane_b32 s44, v253, 56
	v_readlane_b32 s45, v253, 57
	s_add_u32 s80, s44, 0x300000
	v_writelane_b32 v254, s0, 0
	s_addc_u32 s93, s45, 0
	v_readlane_b32 s4, v253, 16
	v_writelane_b32 v254, s1, 1
	v_readlane_b32 s5, v253, 17
	s_add_u32 s0, s4, 0x5000000
	s_addc_u32 s1, s5, 0
	v_writelane_b32 v254, s0, 2
	s_nop 1
	v_writelane_b32 v254, s1, 3
	s_ashr_i32 s0, s96, 31
	s_lshr_b32 s0, s0, 29
	s_add_i32 s0, s96, s0
	s_ashr_i32 s1, s0, 3
	s_and_b32 s0, s0, -8
	s_sub_i32 s0, s96, s0
	s_cmp_lt_i32 s0, 0
	v_writelane_b32 v254, s1, 4
	s_cselect_b64 s[4:5], -1, 0
	v_writelane_b32 v254, s4, 5
	s_nop 1
	v_writelane_b32 v254, s5, 6
	v_writelane_b32 v254, s0, 7
	s_lshr_b32 s0, s0, 31
	s_cmp_lt_u32 s96, 64
	v_writelane_b32 v254, s0, 8
	s_cselect_b64 s[0:1], -1, 0
	v_writelane_b32 v254, s0, 9
	s_nop 1
	v_writelane_b32 v254, s1, 10
	v_writelane_b32 v254, s3, 11
	s_sub_i32 s0, s3, 0x80
	v_writelane_b32 v254, s0, 12
	s_lshl_b32 s0, s96, 9
	s_cmpk_lt_i32 s96, 0x100
	v_writelane_b32 v254, s0, 13
	s_cselect_b64 s[0:1], -1, 0
	s_nop 1
	v_writelane_b32 v254, s0, 14
	s_nop 1
	s_ashr_i32 s4, s96, 5
	v_writelane_b32 v254, s1, 15
	s_and_b32 s0, s96, 3
	s_bfe_u32 s1, s96, 0x30002
	v_writelane_b32 v254, s0, 16
	s_lshl_b32 s3, s0, 11
	s_lshl_b32 s0, s1, 21
	v_readlane_b32 s48, v253, 12
	v_writelane_b32 v254, s1, 17
	v_readlane_b32 s49, v253, 13
	s_add_u32 s20, s48, s0
	s_mov_b32 s0, s4
	s_addc_u32 s21, s49, 0
	s_ashr_i32 s5, s4, 31
	v_writelane_b32 v254, s0, 18
	v_readlane_b32 s10, v253, 22
	v_readlane_b32 s11, v253, 23
	v_writelane_b32 v254, s1, 19
	s_lshl_b64 s[0:1], s[4:5], 13
	s_add_u32 s0, s10, s0
	s_addc_u32 s1, s11, s1
	s_add_u32 s0, s0, s3
	s_addc_u32 s1, s1, 0
	s_add_u32 s4, s20, s3
	s_nop 1
	s_addc_u32 s5, s21, 0
	s_nop 1
	s_add_u32 s8, s0, 0x800000
	s_addc_u32 s9, s1, 0
	v_writelane_b32 v254, s8, 20
	v_readlane_b32 s50, v253, 14
	v_readlane_b32 s51, v253, 15
	v_writelane_b32 v254, s9, 21
	s_add_u32 s8, s4, 0x100000
	v_writelane_b32 v254, s4, 22
	s_addc_u32 s9, s5, 0
	v_readlane_b32 s6, v253, 18
	v_writelane_b32 v254, s5, 23
	v_writelane_b32 v254, s8, 24
	s_add_u32 s4, s0, 0x800080
	v_readlane_b32 s7, v253, 19
	v_writelane_b32 v254, s9, 25
	v_writelane_b32 v254, s0, 26
	s_addc_u32 s5, s1, 0
	s_nop 1
	v_writelane_b32 v254, s1, 27
	v_writelane_b32 v254, s4, 28
	s_not_b32 s0, s96
	s_nop 1
	v_writelane_b32 v254, s5, 29
	v_writelane_b32 v254, s0, 30
	s_add_u32 s0, s50, 0x20000
	s_addc_u32 s1, s51, 0
	v_writelane_b32 v254, s0, 31
	s_nop 1
	v_writelane_b32 v254, s1, 32
	s_add_u32 s0, s6, 0x2000000
	v_writelane_b32 v254, s0, 33
	s_addc_u32 s0, s7, 0
	v_writelane_b32 v254, s0, 34
	s_and_b32 s0, s96, 7
	s_or_b32 s0, s0, 64
	v_writelane_b32 v254, s0, 35
	s_and_b32 s0, s96, 1
	v_writelane_b32 v254, s0, 36
	s_add_u32 s0, s76, 0x200
	s_addc_u32 s1, s77, 0
	s_add_u32 s44, s76, 0x1000
	s_addc_u32 s45, s77, 0
	s_add_u32 s42, s76, 0x1100
	s_nop 1
	s_addc_u32 s43, s77, 0
	s_nop 1
	s_add_u32 s16, s76, 0x1200
	s_nop 1
	s_addc_u32 s17, s77, 0
	s_nop 1
	s_add_u32 s18, s76, 0x1300
	s_addc_u32 s19, s77, 0
	v_writelane_b32 v254, s0, 37
	s_cmp_eq_u32 s2, 15
	s_nop 1
	v_writelane_b32 v254, s1, 38
	s_cselect_b64 s[0:1], -1, 0
	v_writelane_b32 v254, s0, 39
	s_cmp_eq_u32 s2, 14
	s_nop 1
	v_writelane_b32 v254, s1, 40
	s_cselect_b64 s[0:1], -1, 0
	v_writelane_b32 v254, s0, 41
	s_cmp_eq_u32 s2, 13
	s_nop 1
	v_writelane_b32 v254, s1, 42
	s_cselect_b64 s[0:1], -1, 0
	v_writelane_b32 v254, s0, 43
	s_cmp_eq_u32 s2, 12
	s_nop 1
	v_writelane_b32 v254, s1, 44
	s_cselect_b64 s[0:1], -1, 0
	v_writelane_b32 v254, s0, 45
	s_cmp_eq_u32 s2, 11
	v_and_b32_e32 v218, 0xff, v193
	v_writelane_b32 v254, s1, 46
	s_cselect_b64 s[0:1], -1, 0
	v_writelane_b32 v254, s0, 47
	s_cmp_eq_u32 s2, 10
	v_mbcnt_lo_u32_b32 v0, -1, 0
	v_writelane_b32 v254, s1, 48
	s_cselect_b64 s[0:1], -1, 0
	v_writelane_b32 v254, s0, 49
	s_cmp_eq_u32 s2, 9
	v_mbcnt_hi_u32_b32 v228, -1, v0
	v_writelane_b32 v254, s1, 50
	s_cselect_b64 s[0:1], -1, 0
	v_writelane_b32 v254, s0, 51
	s_cmp_eq_u32 s2, 8
	v_and_b32_e32 v0, 64, v228
	v_writelane_b32 v254, s1, 52
	s_cselect_b64 s[0:1], -1, 0
	v_writelane_b32 v254, s0, 53
	s_cmp_eq_u32 s2, 7
	v_mov_b32_e32 v185, 0
	v_writelane_b32 v254, s1, 54
	s_cselect_b64 s[0:1], -1, 0
	v_writelane_b32 v254, s0, 55
	s_cmp_eq_u32 s2, 6
	v_mov_b32_e32 v219, 0x358637bd
	v_writelane_b32 v254, s1, 56
	s_cselect_b64 s[0:1], -1, 0
	v_writelane_b32 v254, s0, 57
	s_cmp_eq_u32 s2, 5
	v_mov_b32_e32 v220, 0xbf1f24be
	v_writelane_b32 v254, s1, 58
	s_cselect_b64 s[0:1], -1, 0
	v_writelane_b32 v254, s0, 59
	s_cmp_eq_u32 s2, 4
	v_mov_b32_e32 v221, 0x3e642e9d
	v_writelane_b32 v254, s1, 60
	s_cselect_b64 s[0:1], -1, 0
	v_writelane_b32 v254, s0, 61
	s_cmp_eq_u32 s2, 3
	v_mov_b32_e32 v222, 0x3ecc95a3
	v_writelane_b32 v254, s1, 62
	s_cselect_b64 s[0:1], -1, 0
	v_writelane_b32 v254, s0, 63
	s_cmp_eq_u32 s2, 2
	v_mov_b32_e32 v223, 0x3c0881c4
	v_writelane_b32 v255, s1, 0
	s_cselect_b64 s[0:1], -1, 0
	v_writelane_b32 v255, s0, 1
	s_cmp_eq_u32 s2, 1
	v_mov_b32_e32 v224, 0xbab64f3b
	v_writelane_b32 v255, s1, 2
	s_cselect_b64 s[0:1], -1, 0
	v_writelane_b32 v255, s0, 3
	s_cmp_eq_u32 s2, 0
	v_mov_b32_e32 v225, 0x23800
	v_writelane_b32 v255, s1, 4
	s_cselect_b64 s[0:1], -1, 0
	v_writelane_b32 v255, s0, 5
	v_mov_b32_e32 v227, 0x23804
	v_mov_b32_e32 v250, 1
	v_writelane_b32 v255, s1, 6
	s_lshl_b32 s0, s2, 8
	s_add_u32 s0, s76, s0
	s_addc_u32 s1, s77, 0
	s_add_u32 s2, s0, 0x1400
	s_addc_u32 s3, s1, 0
	v_writelane_b32 v255, s2, 7
	s_add_u32 s0, s0, 0x2400
	s_addc_u32 s1, s1, 0
	v_writelane_b32 v255, s3, 8
	v_writelane_b32 v255, s0, 9
	v_add_u32_e32 v229, 64, v0
	v_xor_b32_e32 v234, 32, v228
	v_writelane_b32 v255, s1, 10
	s_add_u32 s0, s76, 0x3400
	s_addc_u32 s1, s77, 0
	v_writelane_b32 v255, s0, 11
	v_xor_b32_e32 v235, 1, v228
	v_mov_b32_e32 v236, 0x7fc00000
	v_writelane_b32 v255, s1, 12
	s_add_u32 s0, s76, 0x3500
	s_addc_u32 s1, s77, 0
	v_writelane_b32 v255, s0, 13
	v_mov_b32_e32 v238, 0x7f800000
	v_not_b32_e32 v239, 63
	v_writelane_b32 v255, s1, 14
	s_nop 1
	v_readlane_b32 s8, v253, 40
	s_nop 1
	v_readlane_b32 s9, v253, 41
	s_add_u32 s0, s8, 0x5a000
	s_addc_u32 s1, s9, 0
	v_writelane_b32 v255, s0, 15
	s_nop 1
	v_not_b32_e32 v240, 31
	v_writelane_b32 v255, s1, 16
	s_add_u32 s0, s50, 0x20080
	s_addc_u32 s1, s51, 0
	v_writelane_b32 v255, s0, 17
	v_mov_b32_e32 v241, 0xffc00000
	s_movk_i32 s33, 0x3fff
	v_writelane_b32 v255, s1, 18
	s_lshl_b32 s0, s96, 4
	s_addk_i32 s0, 0xee01
	v_writelane_b32 v255, s0, 19
	s_lshl_b32 s0, s96, 6
	v_writelane_b32 v255, s0, 20
	s_lshl_b32 s0, s96, 8
	v_writelane_b32 v255, s0, 21
	v_writelane_b32 v255, s96, 22
	v_writelane_b32 v255, s72, 23
	s_mov_b32 s36, 0x800000
	s_mov_b32 s70, 0xbfb8aa3b
	v_writelane_b32 v255, s73, 24
	v_writelane_b32 v255, s74, 25
	v_writelane_b32 v255, s75, 26
	v_writelane_b32 v255, s76, 27
	v_writelane_b32 v255, s77, 28
	v_writelane_b32 v255, s78, 29
	v_writelane_b32 v255, s79, 30
	v_writelane_b32 v255, s86, 31
	s_mov_b32 s21, 0x7f800000
	s_movk_i32 s97, 0x7fff
	v_writelane_b32 v255, s87, 32
	v_writelane_b32 v255, s81, 33
	v_writelane_b32 v255, s93, 34
	v_writelane_b32 v255, s16, 35
	s_mov_b32 s71, 0x42ce8ed0
	s_mov_b32 s3, 0xc2b17218
	v_writelane_b32 v255, s17, 36
	v_writelane_b32 v255, s18, 37
	s_mov_b32 s89, 0
	s_mov_b64 s[94:95], 0x1000
	v_writelane_b32 v255, s19, 38
	v_writelane_b32 v255, s42, 39
	s_mov_b64 s[24:25], 0x80
	v_readlane_b32 s37, v253, 1
	v_writelane_b32 v255, s43, 40
	v_writelane_b32 v255, s44, 41
	v_readlane_b32 s38, v253, 2
	v_readlane_b32 s39, v253, 3
	v_writelane_b32 v255, s45, 42
	v_readlane_b32 s40, v253, 4
	v_readlane_b32 s41, v253, 5
	v_readlane_b32 s46, v253, 10
	v_readlane_b32 s47, v253, 11
	s_nop 1
	s_branch .LBB0_24

.LBB0_27:
	s_cmp_eq_u32 s84, 1
	s_mov_b64 s[22:23], -1
	s_cbranch_scc0 .LBB0_36
	v_readlane_b32 s4, v254, 0
	s_waitcnt vmcnt(0)
	v_mov_b32_e32 v0, v218
	v_mov_b32_e32 v1, v218
	v_readlane_b32 s5, v254, 1
	s_load_dword s22, s[4:5], 0x0
	v_readfirstlane_b32 s20, v193
	s_lshr_b32 s20, s20, 6
	s_and_b32 s20, s20, 0x3fffffc
	s_add_i32 s20, s20, s81
	v_ashrrev_i32_e32 v1, 6, v1
	v_add_u32_e32 v1, s20, v1
	s_waitcnt lgkmcnt(0)
	s_lshl_b32 s20, s22, 3
	s_abs_i32 s28, s20
	v_cvt_f32_u32_e32 v2, s28
	s_nop 1
	v_readlane_b32 s16, v253, 44
	v_readlane_b32 s17, v253, 45
	v_rcp_iflag_f32_e32 v2, v2
	s_mov_b64 s[34:35], s[16:17]
	s_mov_b64 s[30:31], s[50:51]
	s_mov_b64 s[26:27], s[48:49]
	v_mul_f32_e32 v2, 0x4f7ffffe, v2
	s_mov_b64 s[22:23], s[74:75]
	v_cvt_u32_f32_e32 v2, v2
	s_add_i32 s26, s20, 0x47ff
	s_xor_b32 s27, s26, s20
	s_sub_i32 s20, 0xffffb801, s20
	s_max_i32 s20, s26, s20
	s_sub_i32 s26, 0, s28
	v_readfirstlane_b32 s29, v2
	s_mul_i32 s26, s26, s29
	s_mul_hi_u32 s26, s29, s26
	s_add_i32 s29, s29, s26
	s_mul_hi_u32 s26, s20, s29
	s_mul_i32 s29, s26, s28
	s_sub_i32 s20, s20, s29
	s_ashr_i32 s27, s27, 31
	s_add_i32 s29, s26, 1
	s_sub_i32 s33, s20, s28
	s_cmp_ge_u32 s20, s28
	s_cselect_b32 s26, s29, s26
	s_cselect_b32 s20, s33, s20
	s_add_i32 s29, s26, 1
	s_cmp_ge_u32 s20, s28
	s_cselect_b32 s20, s29, s26
	s_xor_b32 s20, s20, s27
	s_sub_i32 s20, s20, s27
	v_mul_lo_u32 v64, s20, v1
	v_add_u32_e32 v1, s20, v64
	v_min_i32_e32 v78, 0x4800, v1
	s_movk_i32 s33, 0x3fff
	v_cmp_lt_i32_e32 vcc, v64, v78
	s_nop 1
	s_and_saveexec_b64 s[28:29], vcc
	s_cbranch_execz .LBB0_35
	v_lshlrev_b32_e32 v0, 3, v0
	v_and_b32_e32 v16, 0x1f8, v0
	v_lshlrev_b32_e32 v184, 2, v16
	v_lshl_add_u64 v[12:13], s[34:35], 0, v[184:185]
	flat_load_dwordx4 v[0:3], v[12:13]
	flat_load_dwordx4 v[4:7], v[12:13] offset:16
	flat_load_dwordx4 v[8:11], v[12:13] offset:2048
	s_nop 0
	flat_load_dwordx4 v[12:15], v[12:13] offset:2064
	v_cmp_lt_i32_e32 vcc, v234, v229
	v_ashrrev_i32_e32 v65, 31, v64
	v_readlane_b32 s4, v253, 32
	v_cndmask_b32_e32 v17, v228, v234, vcc
	v_lshlrev_b32_e32 v79, 2, v17
	v_xor_b32_e32 v17, 16, v228
	v_cmp_lt_i32_e32 vcc, v17, v229
	v_or_b32_e32 v18, 4, v16
	v_or_b32_e32 v20, 0x200, v16
	v_cndmask_b32_e32 v17, v228, v17, vcc
	v_lshlrev_b32_e32 v80, 2, v17
	v_xor_b32_e32 v17, 8, v228
	v_cmp_lt_i32_e32 vcc, v17, v229
	v_or_b32_e32 v22, 0x204, v16
	v_lshlrev_b32_e32 v184, 1, v16
	v_cndmask_b32_e32 v17, v228, v17, vcc
	v_lshlrev_b32_e32 v81, 2, v17
	v_xor_b32_e32 v17, 4, v228
	v_cmp_lt_i32_e32 vcc, v17, v229
	v_lshlrev_b64 v[24:25], 12, v[64:65]
	v_readlane_b32 s5, v253, 33
	v_cndmask_b32_e32 v17, v228, v17, vcc
	v_lshlrev_b32_e32 v82, 2, v17
	v_xor_b32_e32 v17, 2, v228
	v_cmp_lt_i32_e32 vcc, v17, v229
	v_lshl_add_u64 v[66:67], s[30:31], 0, v[184:185]
	v_mov_b32_e32 v71, -1
	v_cndmask_b32_e32 v17, v228, v17, vcc
	v_cmp_lt_i32_e32 vcc, v235, v229
	v_lshlrev_b32_e32 v83, 2, v17
	v_lshl_add_u64 v[68:69], s[4:5], 0, v[24:25]
	v_cndmask_b32_e32 v17, v228, v235, vcc
	v_lshlrev_b32_e32 v84, 2, v17
	s_mov_b64 s[30:31], 0
	v_lshlrev_b32_e32 v70, 2, v18
	v_lshlrev_b32_e32 v72, 2, v20
	v_lshlrev_b32_e32 v74, 2, v22
	v_lshlrev_b32_e32 v184, 2, v16
	s_nop 1
	s_branch .LBB0_31

.LBB0_33:
	s_or_b64 exec, exec, s[34:35]
	v_cmp_lt_i32_e32 vcc, s33, v64
	v_mov_b64_e32 v[76:77], v[64:65]
	v_mov_b64_e32 v[48:49], v[68:69]
	s_and_saveexec_b64 s[34:35], vcc
	s_cbranch_execz .LBB0_30
	v_add_u32_e32 v48, 0xffffc000, v64
	v_mov_b32_e32 v49, v185
	s_nop 1
	v_lshlrev_b64 v[48:49], 12, v[48:49]
	v_readlane_b32 s8, v253, 36
	v_readlane_b32 s9, v253, 37
	v_mov_b32_e32 v76, v64
	v_mov_b32_e32 v77, v185
	v_lshl_add_u64 v[48:49], s[8:9], 0, v[48:49]
	s_nop 1
	s_branch .LBB0_30

.LBB0_38:
	s_add_i32 s0, s84, -2
	s_mul_hi_i32 s1, s0, 0x66666667
	s_lshr_b32 s20, s1, 31
	s_ashr_i32 s1, s1, 2
	s_add_i32 s4, s1, s20
	s_mul_i32 s1, s4, 10
	s_sub_i32 s91, s0, s1
	s_mov_b32 s92, s4
	s_cmp_lt_i32 s91, 4
	s_mov_b64 s[0:1], -1
	s_cbranch_scc1 .LBB0_188
	s_cmp_lt_i32 s91, 7
	s_cbranch_scc1 .LBB0_54
	s_cmp_gt_i32 s91, 7
	s_cbranch_scc0 .LBB0_55
	s_cmp_gt_i32 s91, 8
	s_cbranch_scc0 .LBB0_56
	s_cmp_eq_u32 s91, 9
	s_cbranch_scc0 .LBB0_58
	v_readlane_b32 s4, v254, 0
	s_waitcnt vmcnt(0)
	v_mov_b32_e32 v0, v218
	v_mov_b32_e32 v1, v218
	v_readlane_b32 s5, v254, 1
	s_load_dword s1, s[4:5], 0x0
	v_readfirstlane_b32 s0, v193
	s_lshr_b32 s0, s0, 6
	s_and_b32 s0, s0, 0x3fffffc
	s_add_i32 s0, s0, s81
	s_waitcnt lgkmcnt(0)
	s_lshl_b32 s20, s1, 3
	s_cmp_lt_i32 s84, 32
	v_ashrrev_i32_e32 v1, 6, v1
	s_cselect_b64 s[38:39], -1, 0
	v_add_u32_e32 v1, s0, v1
	s_and_b64 s[0:1], s[38:39], exec
	s_movk_i32 s0, 0x4000
	s_cselect_b32 s22, 0x4800, s0
	s_abs_i32 s23, s20
	v_cvt_f32_u32_e32 v2, s23
	s_add_i32 s26, s22, s20
	s_add_i32 s27, s26, -1
	s_sub_i32 s26, 1, s26
	v_rcp_iflag_f32_e32 v2, v2
	s_xor_b32 s20, s27, s20
	s_max_i32 s26, s27, s26
	s_sub_i32 s27, 0, s23
	v_mul_f32_e32 v2, 0x4f7ffffe, v2
	v_cvt_u32_f32_e32 v2, v2
	s_ashr_i32 s20, s20, 31
	s_nop 1
	v_readlane_b32 s16, v253, 44
	v_readfirstlane_b32 s28, v2
	s_mul_i32 s27, s27, s28
	s_mul_hi_u32 s27, s28, s27
	s_add_i32 s28, s28, s27
	s_mul_hi_u32 s27, s26, s28
	s_mul_i32 s28, s27, s23
	s_sub_i32 s26, s26, s28
	s_add_i32 s28, s27, 1
	s_sub_i32 s29, s26, s23
	s_cmp_ge_u32 s26, s23
	s_cselect_b32 s27, s28, s27
	s_cselect_b32 s26, s29, s26
	s_add_i32 s28, s27, 1
	s_cmp_ge_u32 s26, s23
	s_cselect_b32 s23, s28, s27
	s_xor_b32 s23, s23, s20
	s_sub_i32 s20, s23, s20
	v_mul_lo_u32 v104, s20, v1
	v_add_u32_e32 v1, s20, v104
	v_readlane_b32 s17, v253, 45
	v_min_i32_e32 v107, s22, v1
	s_mov_b64 s[0:1], s[74:75]
	s_mov_b64 s[36:37], s[16:17]
	s_mov_b64 s[30:31], s[50:51]
	s_mov_b64 s[34:35], s[48:49]
	v_cmp_lt_i32_e32 vcc, v104, v107
	s_nop 1
	s_and_saveexec_b64 s[22:23], vcc
	s_cbranch_execz .LBB0_57
	s_sub_i32 s20, s84, 32
	s_cmp_gt_u32 s20, 9
	v_cndmask_b32_e64 v1, 0, 1, s[38:39]
	s_cselect_b64 s[28:29], -1, 0
	v_readfirstlane_b32 s20, v1
	s_mov_b32 s4, s92
	s_ashr_i32 s5, s92, 31
	s_add_i32 s26, s92, s20
	s_lshl_b64 s[38:39], s[4:5], 14
	s_add_u32 s20, s36, s38
	s_addc_u32 s27, s37, s39
	s_add_u32 s38, s20, 0x3000
	v_lshlrev_b32_e32 v0, 3, v0
	s_addc_u32 s39, s27, 0
	s_ashr_i32 s27, s26, 31
	v_and_b32_e32 v106, 0x1f8, v0
	s_lshl_b64 s[40:41], s[26:27], 14
	v_or_b32_e32 v32, 4, v106
	s_add_u32 s36, s36, s40
	v_lshlrev_b32_e32 v8, 2, v32
	v_mov_b32_e32 v9, v185
	v_or_b32_e32 v34, 0x200, v106
	v_or_b32_e32 v36, 0x204, v106
	s_addc_u32 s37, s37, s41
	v_lshlrev_b32_e32 v184, 2, v106
	v_lshl_add_u64 v[24:25], s[38:39], 0, v[8:9]
	v_lshlrev_b32_e32 v8, 2, v34
	v_lshlrev_b32_e32 v18, 2, v36
	v_mov_b32_e32 v19, v185
	v_lshl_add_u64 v[0:1], s[38:39], 0, v[184:185]
	v_lshl_add_u64 v[28:29], s[36:37], 0, v[184:185]
	v_lshl_add_u64 v[16:17], s[38:39], 0, v[8:9]
	v_lshl_add_u64 v[20:21], s[38:39], 0, v[18:19]
	flat_load_dwordx4 v[0:3], v[0:1]
	s_nop 0
	flat_load_dwordx4 v[4:7], v[28:29]
	flat_load_dwordx4 v[8:11], v[28:29] offset:16
	flat_load_dwordx4 v[12:15], v[28:29] offset:2048
	s_nop 0
	flat_load_dwordx4 v[16:19], v[16:17]
	s_nop 0
	flat_load_dwordx4 v[20:23], v[20:21]
	s_nop 0
	flat_load_dwordx4 v[24:27], v[24:25]
	s_nop 0
	flat_load_dwordx4 v[28:31], v[28:29] offset:2064
	v_cmp_lt_i32_e32 vcc, v234, v229
	v_lshlrev_b32_e32 v38, 1, v106
	v_mov_b32_e32 v39, v185
	v_cndmask_b32_e32 v33, v228, v234, vcc
	v_lshlrev_b32_e32 v126, 2, v33
	v_xor_b32_e32 v33, 16, v228
	v_cmp_lt_i32_e32 vcc, v33, v229
	s_mul_i32 s20, s26, 9
	v_lshl_add_u64 v[108:109], s[34:35], 0, v[38:39]
	v_cndmask_b32_e32 v33, v228, v33, vcc
	v_lshlrev_b32_e32 v127, 2, v33
	v_xor_b32_e32 v33, 8, v228
	v_cmp_lt_i32_e32 vcc, v33, v229
	v_lshl_add_u64 v[110:111], s[30:31], 0, v[38:39]
	v_lshl_add_u64 v[38:39], s[0:1], 0, v[184:185]
	v_cndmask_b32_e32 v33, v228, v33, vcc
	v_lshlrev_b32_e32 v128, 2, v33
	v_xor_b32_e32 v33, 4, v228
	v_cmp_lt_i32_e32 vcc, v33, v229
	s_mov_b64 s[26:27], 0x5000
	v_ashrrev_i32_e32 v105, 31, v104
	v_cndmask_b32_e32 v33, v228, v33, vcc
	v_lshlrev_b32_e32 v129, 2, v33
	v_xor_b32_e32 v33, 2, v228
	v_cmp_lt_i32_e32 vcc, v33, v229
	v_readlane_b32 s4, v253, 0
	v_lshl_add_u64 v[112:113], v[38:39], 0, s[26:27]
	v_cndmask_b32_e32 v33, v228, v33, vcc
	v_cmp_lt_i32_e32 vcc, v235, v229
	v_lshlrev_b32_e32 v130, 2, v33
	v_lshlrev_b64 v[38:39], 12, v[104:105]
	v_cndmask_b32_e32 v33, v228, v235, vcc
	v_readlane_b32 s5, v253, 1
	s_nop 1
	v_mov_b32_e32 v117, -1
	v_lshlrev_b32_e32 v131, 2, v33
	s_movk_i32 s6, 0x1800
	v_lshl_add_u64 v[114:115], s[4:5], 0, v[38:39]
	s_mov_b64 s[30:31], 0
	v_lshlrev_b32_e32 v116, 2, v32
	v_lshlrev_b32_e32 v118, 2, v34
	v_lshlrev_b32_e32 v120, 2, v36
	s_nop 1
	s_branch .LBB0_46

.LBB0_72:
	s_cmp_gt_i32 s91, 5
	s_mov_b64 s[0:1], -1
	s_cbranch_scc0 .LBB0_81
	v_readlane_b32 s4, v254, 0
	s_waitcnt vmcnt(0)
	v_mov_b32_e32 v0, v218
	v_mov_b32_e32 v1, v218
	v_readlane_b32 s5, v254, 1
	s_load_dword s1, s[4:5], 0x0
	v_readfirstlane_b32 s0, v193
	s_lshr_b32 s0, s0, 6
	s_and_b32 s0, s0, 0x3fffffc
	s_add_i32 s0, s0, s81
	v_ashrrev_i32_e32 v1, 6, v1
	v_add_u32_e32 v1, s0, v1
	s_waitcnt lgkmcnt(0)
	s_lshl_b32 s0, s1, 3
	s_cmp_lt_i32 s84, 32
	s_movk_i32 s1, 0x4000
	s_cselect_b32 s1, 0x4800, s1
	s_abs_i32 s20, s0
	v_cvt_f32_u32_e32 v2, s20
	s_add_i32 s26, s1, s0
	s_add_i32 s27, s26, -1
	s_sub_i32 s26, 1, s26
	v_rcp_iflag_f32_e32 v2, v2
	s_xor_b32 s0, s27, s0
	s_max_i32 s26, s27, s26
	s_sub_i32 s27, 0, s20
	v_mul_f32_e32 v2, 0x4f7ffffe, v2
	v_cvt_u32_f32_e32 v2, v2
	s_ashr_i32 s0, s0, 31
	s_nop 1
	v_readlane_b32 s16, v253, 44
	v_readfirstlane_b32 s33, v2
	s_mul_i32 s27, s27, s33
	s_mul_hi_u32 s27, s33, s27
	s_add_i32 s33, s33, s27
	s_mul_hi_u32 s27, s26, s33
	s_mul_i32 s33, s27, s20
	s_sub_i32 s26, s26, s33
	s_add_i32 s33, s27, 1
	s_sub_i32 s36, s26, s20
	s_cmp_ge_u32 s26, s20
	s_cselect_b32 s27, s33, s27
	s_cselect_b32 s26, s36, s26
	s_add_i32 s33, s27, 1
	s_cmp_ge_u32 s26, s20
	s_cselect_b32 s20, s33, s27
	s_xor_b32 s20, s20, s0
	s_sub_i32 s0, s20, s0
	v_mul_lo_u32 v80, s0, v1
	v_add_u32_e32 v1, s0, v80
	v_readlane_b32 s17, v253, 45
	v_min_i32_e32 v83, s1, v1
	s_mov_b64 s[28:29], s[50:51]
	s_mov_b64 s[34:35], s[48:49]
	s_mov_b64 s[30:31], s[74:75]
	s_mov_b64 s[22:23], s[16:17]
	s_movk_i32 s33, 0x3fff
	v_cmp_lt_i32_e32 vcc, v80, v83
	s_nop 1
	s_and_saveexec_b64 s[0:1], vcc
	v_readlane_b32 s36, v253, 0
	v_readlane_b32 s37, v253, 1
	v_readlane_b32 s38, v253, 2
	v_readlane_b32 s39, v253, 3
	v_readlane_b32 s40, v253, 4
	v_readlane_b32 s41, v253, 5
	v_readlane_b32 s42, v253, 6
	v_readlane_b32 s43, v253, 7
	v_readlane_b32 s44, v253, 8
	v_readlane_b32 s45, v253, 9
	v_readlane_b32 s46, v253, 10
	v_readlane_b32 s47, v253, 11
	s_nop 1
	s_cbranch_execz .LBB0_80
	s_mov_b32 s4, s92
	s_ashr_i32 s5, s92, 31
	s_lshl_b64 s[26:27], s[4:5], 14
	s_add_u32 s20, s22, s26
	s_addc_u32 s27, s23, s27
	s_add_u32 s22, s20, 0x1000
	v_lshlrev_b32_e32 v0, 3, v0
	s_addc_u32 s23, s27, 0
	v_and_b32_e32 v82, 0x1f8, v0
	s_add_u32 s26, s20, 0x2000
	v_or_b32_e32 v32, 4, v82
	v_or_b32_e32 v34, 0x200, v82
	v_or_b32_e32 v36, 0x204, v82
	s_addc_u32 s27, s27, 0
	v_lshlrev_b32_e32 v184, 2, v82
	v_lshlrev_b32_e32 v8, 2, v32
	v_mov_b32_e32 v9, v185
	v_lshlrev_b32_e32 v16, 2, v34
	v_mov_b32_e32 v17, v185
	v_lshlrev_b32_e32 v24, 2, v36
	v_mov_b32_e32 v25, v185
	v_lshl_add_u64 v[0:1], s[22:23], 0, v[184:185]
	v_lshl_add_u64 v[4:5], s[26:27], 0, v[184:185]
	v_lshl_add_u64 v[10:11], s[22:23], 0, v[8:9]
	v_lshl_add_u64 v[12:13], s[26:27], 0, v[8:9]
	v_lshl_add_u64 v[18:19], s[22:23], 0, v[16:17]
	v_lshl_add_u64 v[20:21], s[26:27], 0, v[16:17]
	v_lshl_add_u64 v[26:27], s[22:23], 0, v[24:25]
	v_lshl_add_u64 v[28:29], s[26:27], 0, v[24:25]
	s_waitcnt vmcnt(0)
	flat_load_dwordx4 v[0:3], v[0:1]
	s_nop 0
	flat_load_dwordx4 v[4:7], v[4:5]
	s_nop 0
	flat_load_dwordx4 v[8:11], v[10:11]
	s_nop 0
	flat_load_dwordx4 v[12:15], v[12:13]
	s_nop 0
	flat_load_dwordx4 v[16:19], v[18:19]
	s_nop 0
	flat_load_dwordx4 v[20:23], v[20:21]
	s_nop 0
	flat_load_dwordx4 v[24:27], v[26:27]
	s_nop 0
	flat_load_dwordx4 v[28:31], v[28:29]
	v_cmp_lt_i32_e32 vcc, v234, v229
	s_add_i32 s20, s84, 7
	s_add_u32 s22, s30, 0x3000
	v_cndmask_b32_e32 v33, v228, v234, vcc
	v_lshlrev_b32_e32 v106, 2, v33
	v_xor_b32_e32 v33, 16, v228
	v_cmp_lt_i32_e32 vcc, v33, v229
	s_addc_u32 s23, s31, 0
	v_lshlrev_b32_e32 v38, 1, v82
	v_cndmask_b32_e32 v33, v228, v33, vcc
	v_lshlrev_b32_e32 v107, 2, v33
	v_xor_b32_e32 v33, 8, v228
	v_cmp_lt_i32_e32 vcc, v33, v229
	v_mov_b32_e32 v39, v185
	v_readlane_b32 s4, v253, 32
	v_cndmask_b32_e32 v33, v228, v33, vcc
	v_lshlrev_b32_e32 v108, 2, v33
	v_xor_b32_e32 v33, 4, v228
	v_cmp_lt_i32_e32 vcc, v33, v229
	s_cmp_lt_u32 s20, 19
	v_lshl_add_u64 v[84:85], s[34:35], 0, v[38:39]
	v_cndmask_b32_e32 v33, v228, v33, vcc
	v_lshlrev_b32_e32 v109, 2, v33
	v_xor_b32_e32 v33, 2, v228
	v_cmp_lt_i32_e32 vcc, v33, v229
	v_lshl_add_u64 v[86:87], s[28:29], 0, v[38:39]
	v_readlane_b32 s5, v253, 33
	v_cndmask_b32_e32 v33, v228, v33, vcc
	v_cmp_lt_i32_e32 vcc, v235, v229
	v_lshl_add_u64 v[38:39], s[30:31], 0, v[184:185]
	s_mov_b64 s[30:31], 0x2000
	v_ashrrev_i32_e32 v81, 31, v80
	v_lshlrev_b32_e32 v110, 2, v33
	v_cndmask_b32_e32 v33, v228, v235, vcc
	s_nop 1
	v_readlane_b32 s8, v253, 36
	v_readlane_b32 s9, v253, 37
	s_cselect_b32 s27, s5, s37
	s_cselect_b32 s26, s4, s36
	v_lshl_add_u64 v[88:89], v[38:39], 0, s[30:31]
	v_lshlrev_b64 v[38:39], 12, v[80:81]
	v_mov_b32_e32 v95, -1
	v_lshlrev_b32_e32 v111, 2, v33
	s_movk_i32 s6, 0x1800
	s_cselect_b32 s29, s9, s73
	s_cselect_b32 s28, s8, s72
	v_lshl_add_u64 v[90:91], s[26:27], 0, v[38:39]
	v_lshl_add_u64 v[92:93], s[36:37], 0, v[38:39]
	s_mov_b64 s[30:31], 0
	v_lshlrev_b32_e32 v94, 2, v32
	v_lshlrev_b32_e32 v96, 2, v34
	v_lshlrev_b32_e32 v98, 2, v36
	s_nop 1
	s_branch .LBB0_76

.LBB0_149:
	s_cmp_gt_i32 s84, 31
	v_readlane_b32 s4, v254, 9
	s_cselect_b64 s[0:1], -1, 0
	v_readlane_b32 s5, v254, 10
	s_or_b64 s[0:1], s[0:1], s[4:5]
	s_and_b64 vcc, exec, s[0:1]
	s_cbranch_vccnz .LBB0_187
	s_cmp_eq_u32 s91, 5
	s_movk_i32 s0, 0xd48
	s_cselect_b32 s20, s0, 0xe74
	s_movk_i32 s0, 0x1080
	v_readfirstlane_b32 s22, v193
	s_cselect_b32 s23, 0xe74, s0
	s_and_b64 s[0:1], s[56:57], exec
	s_cselect_b32 s26, 0, s20
	s_lshr_b32 s22, s22, 8
	s_and_b64 s[0:1], s[56:57], exec
	v_readlane_b32 s0, v254, 12
	s_cselect_b32 s20, 0xd48, s23
	s_add_i32 s0, s0, s26
	s_add_i32 s50, s0, s22
	s_waitcnt vmcnt(0)
	v_mov_b32_e32 v1, v218
	s_cmp_ge_i32 s50, s20
	s_waitcnt vmcnt(0) lgkmcnt(0)
	s_barrier
	s_cbranch_scc1 .LBB0_187
	v_readlane_b32 s0, v254, 0
	v_readlane_b32 s1, v254, 1
	s_load_dword s0, s[0:1], 0x0
	s_add_i32 s28, s92, 1
	s_nop 1
	v_readlane_b32 s54, v253, 2
	v_readlane_b32 s55, v253, 3
	s_waitcnt lgkmcnt(0)
	s_lshl_b32 s0, s0, 1
	s_sub_i32 s51, s0, 0x80
	s_bitcmp1_b32 s28, 0
	s_cselect_b32 s0, 0x2180000, 0
	s_add_u32 s38, s54, s0
	v_readlane_b32 s56, v253, 4
	s_addc_u32 s39, s55, 0
	v_readlane_b32 s57, v253, 5
	s_add_u32 s40, s56, s0
	v_readlane_b32 s58, v253, 6
	s_addc_u32 s41, s57, 0
	v_cvt_f32_i32_e32 v7, v1
	v_readlane_b32 s59, v253, 7
	s_add_u32 s42, s58, s0
	v_readlane_b32 s60, v253, 8
	s_addc_u32 s43, s59, 0
	v_readlane_b32 s61, v253, 9
	s_add_u32 s44, s60, s0
	v_readlane_b32 s62, v253, 10
	s_addc_u32 s45, s61, 0
	v_mul_f32_e32 v7, 0x3d000000, v7
	v_readlane_b32 s63, v253, 11
	s_add_u32 s46, s62, s0
	s_nop 1
	v_mul_f32_e64 v8, |v7|, 0.5
	s_mul_i32 s22, s28, 0x1900000
	s_addc_u32 s47, s63, 0
	s_ashr_i32 s29, s28, 31
	v_readlane_b32 s18, v253, 46
	v_fract_f32_e32 v9, v8
	s_mul_hi_i32 s1, s28, 0x1900000
	v_readlane_b32 s19, v253, 47
	s_add_u32 s48, s18, s22
	v_add_f32_e32 v9, v9, v9
	v_cmp_neq_f32_e32 vcc, s21, v8
	s_addc_u32 s49, s19, s1
	v_cmp_gt_f32_e64 s[0:1], |v7|, 1.0
	v_cndmask_b32_e32 v8, 0, v9, vcc
	s_nop 1
	v_cndmask_b32_e64 v8, |v7|, v8, s[0:1]
	v_add_f32_e32 v9, v8, v8
	v_rndne_f32_e32 v9, v9
	v_fmac_f32_e32 v8, -0.5, v9
	v_mul_f32_e32 v11, v8, v8
	v_fmamk_f32 v12, v11, 0x3e75aa41, v220
	v_fmaak_f32 v12, v11, v12, 0x40234736
	v_fmaak_f32 v12, v11, v12, 0xc0a55e0e
	v_mul_f32_e32 v13, v8, v11
	v_mul_f32_e32 v12, v13, v12
	v_cvt_i32_f32_e32 v10, v9
	v_fmac_f32_e32 v12, 0x40490fdb, v8
	v_fmamk_f32 v8, v11, 0x3d4be544, v221
	v_fmaak_f32 v8, v11, v8, 0xbfaad1da
	v_fmaak_f32 v8, v11, v8, 0x4081e0d3
	v_fmaak_f32 v8, v11, v8, 0xc09de9e6
	v_fma_f32 v8, v11, v8, 1.0
	v_and_b32_e32 v11, 1, v10
	s_nop 1
	v_lshlrev_b32_e32 v6, 2, v1
	v_cmp_eq_u32_e32 vcc, 0, v11
	s_nop 1
	v_ashrrev_i32_e32 v0, 4, v1
	v_and_b32_e32 v2, 60, v6
	v_and_b32_e32 v34, 63, v1
	v_ashrrev_i32_e32 v35, 2, v1
	v_cmp_gt_i32_e64 s[36:37], 64, v1
	v_and_b32_e32 v1, 0x7fffffff, v7
	v_and_b32_e32 v9, 2, v10
	v_cndmask_b32_e64 v11, -v12, v8, vcc
	v_add_u32_e32 v39, s2, v6
	v_cndmask_b32_e32 v6, v8, v12, vcc
	v_lshlrev_b32_e32 v8, 30, v10
	s_lshl_b64 s[22:23], s[28:29], 22
	v_readlane_b32 s60, v253, 56
	v_cmp_eq_u32_e64 s[0:1], 0, v9
	v_and_b32_e32 v8, 0x80000000, v8
	v_xor_b32_e32 v1, v1, v7
	s_nop 1
	v_readlane_b32 s61, v253, 57
	s_add_u32 s52, s60, s22
	v_cndmask_b32_e64 v9, -v11, v11, s[0:1]
	s_movk_i32 s0, 0x1f8
	v_xor_b32_e32 v1, v1, v8
	s_addc_u32 s53, s61, s23
	s_lshl_b64 s[34:35], s[28:29], 16
	s_lshl_b64 s[30:31], s[28:29], 10
	v_cmp_class_f32_e64 s[0:1], v7, s0
	v_xor_b32_e32 v1, v1, v6
	s_nop 1
	s_add_u32 s29, s52, 0x300000
	v_and_b32_e32 v3, -16, v35
	v_cndmask_b32_e64 v38, v236, v9, s[0:1]
	v_cndmask_b32_e64 v40, v236, v1, s[0:1]
	s_movk_i32 s0, 0x41
	v_readlane_b32 s56, v253, 52
	s_addc_u32 s54, s53, 0
	v_mad_u64_u32 v[10:11], s[0:1], v0, s0, v[2:3]
	v_readlane_b32 s57, v253, 53
	s_add_u32 s0, s56, s34
	v_readlane_b32 s58, v253, 54
	s_addc_u32 s1, s57, s35
	s_nop 1
	v_readlane_b32 s59, v253, 55
	s_add_u32 s26, s58, s30
	v_readlane_b32 s66, v253, 62
	s_mul_i32 s55, s28, 0xb00000
	s_addc_u32 s27, s59, s31
	v_readlane_b32 s67, v253, 63
	s_mul_hi_i32 s33, s28, 0xb00000
	s_mul_hi_i32 s60, s28, 0x1600000
	s_mul_i32 s61, s28, 0x1600000
	s_add_u32 s28, s66, s55
	v_readlane_b32 s64, v253, 60
	s_addc_u32 s30, s67, s33
	v_readlane_b32 s65, v253, 61
	s_add_u32 s31, s64, s61
	v_readlane_b32 s62, v253, 58
	v_lshlrev_b32_e32 v184, 1, v34
	v_mov_b32_e32 v36, s2
	v_ashrrev_i32_e32 v1, 31, v0
	v_add_u32_e32 v12, 16, v0
	s_addc_u32 s34, s65, s60
	v_readlane_b32 s63, v253, 59
	v_lshl_add_u64 v[4:5], s[40:41], 0, v[184:185]
	v_lshl_add_u64 v[6:7], s[38:39], 0, v[184:185]
	v_lshl_add_u32 v41, v10, 2, s2
	v_lshlrev_b64 v[10:11], 12, v[0:1]
	v_ashrrev_i32_e32 v13, 31, v12
	v_add_u32_e32 v18, 32, v0
	v_add_u32_e32 v24, 48, v0
	v_lshlrev_b32_e32 v184, 2, v2
	v_mad_u32_u24 v1, v34, s90, v36
	s_add_u32 s22, s62, s22
	v_lshrrev_b32_e32 v34, 4, v35
	v_lshlrev_b32_e32 v8, 6, v0
	v_lshlrev_b32_e32 v14, 6, v12
	v_lshlrev_b64 v[16:17], 12, v[12:13]
	v_lshlrev_b32_e32 v20, 6, v18
	v_ashrrev_i32_e32 v19, 31, v18
	v_lshlrev_b32_e32 v26, 6, v24
	v_ashrrev_i32_e32 v25, 31, v24
	v_lshl_add_u64 v[30:31], s[0:1], 0, v[184:185]
	s_addc_u32 s23, s63, s23
	v_lshlrev_b32_e32 v13, 6, v34
	s_add_i32 s0, s2, 0x4100
	v_ashrrev_i32_e32 v9, 31, v8
	v_ashrrev_i32_e32 v15, 31, v14
	v_ashrrev_i32_e32 v21, 31, v20
	v_lshlrev_b64 v[22:23], 12, v[18:19]
	v_ashrrev_i32_e32 v27, 31, v26
	v_lshlrev_b64 v[28:29], 12, v[24:25]
	v_lshl_add_u64 v[32:33], s[26:27], 0, v[184:185]
	s_movk_i32 s33, 0x3fff
	v_add_u32_e32 v19, s0, v13
	v_lshlrev_b32_e32 v25, 5, v34
	v_mul_lo_u32 v42, v34, 48
	s_nop 1
	s_branch .LBB0_153

.LBB0_187:
	v_readlane_b32 s48, v253, 16
	s_mov_b64 s[0:1], 0
	v_readlane_b32 s50, v253, 18
	v_readlane_b32 s51, v253, 19
	v_readlane_b32 s52, v253, 20
	v_readlane_b32 s53, v253, 21
	v_readlane_b32 s56, v253, 24
	v_readlane_b32 s57, v253, 25
	s_mov_b32 s36, 0x800000
	v_readlane_b32 s49, v253, 17
	v_readlane_b32 s54, v253, 22
	v_readlane_b32 s55, v253, 23
	s_nop 1

.LBB0_198:
	s_and_b32 s26, s26, 3
	s_or_b32 s28, s26, s31
	v_readlane_b32 s40, v253, 48
	v_ashrrev_i32_e32 v64, 1, v100
	s_ashr_i32 s29, s28, 31
	s_nop 1
	s_waitcnt vmcnt(0)
	v_add_u32_e32 v0, s20, v64
	s_lshl_b64 s[28:29], s[28:29], 2
	v_ashrrev_i32_e32 v1, 31, v0
	v_readlane_b32 s48, v253, 16
	v_readlane_b32 s41, v253, 49
	s_add_u32 s28, s40, s28
	v_lshlrev_b64 v[0:1], 12, v[0:1]
	v_readlane_b32 s49, v253, 17
	s_addc_u32 s29, s41, s29
	v_and_b32_e32 v62, 1, v100
	v_lshl_add_u64 v[0:1], s[48:49], 0, v[0:1]
	s_lshl_b32 s88, s26, 7
	v_lshlrev_b32_e32 v184, 6, v62
	v_lshl_add_u64 v[0:1], v[0:1], 0, s[88:89]
	v_lshl_add_u64 v[12:13], v[0:1], 0, v[184:185]
	global_load_dwordx4 v[0:3], v[12:13], off
	global_load_dwordx4 v[4:7], v[12:13], off offset:16
	global_load_dwordx4 v[8:11], v[12:13], off offset:32
	global_load_dwordx4 v[26:29], v[12:13], off offset:48
	global_load_dword v65, v185, s[28:29]
	global_load_dword v63, v185, s[28:29] offset:16
	v_cndmask_b32_e64 v15, 0, 1, s[22:23]
	v_add_u32_e32 v14, s27, v64
	v_cmp_ne_u32_e64 s[36:37], 1, v15
	v_ashrrev_i32_e32 v15, 31, v14
	v_readlane_b32 s60, v253, 28
	v_readlane_b32 s61, v253, 29
	v_lshlrev_b64 v[14:15], 8, v[14:15]
	v_readlane_b32 s50, v253, 18
	v_lshl_add_u64 v[14:15], s[60:61], 0, v[14:15]
	v_readlane_b32 s51, v253, 19
	v_readlane_b32 s52, v253, 20
	v_readlane_b32 s53, v253, 21
	v_readlane_b32 s54, v253, 22
	v_readlane_b32 s55, v253, 23
	v_readlane_b32 s56, v253, 24
	v_readlane_b32 s57, v253, 25
	v_readlane_b32 s58, v253, 26
	v_readlane_b32 s59, v253, 27
	s_nop 1
	v_lshl_add_u64 v[18:19], v[14:15], 0, v[184:185]
	s_andn2_b64 vcc, exec, s[22:23]
	v_readlane_b32 s42, v253, 50
	v_readlane_b32 s43, v253, 51
	v_readlane_b32 s44, v253, 52
	v_readlane_b32 s45, v253, 53
	v_readlane_b32 s46, v253, 54
	v_readlane_b32 s47, v253, 55
	s_waitcnt vmcnt(0)
	v_lshlrev_b32_e32 v58, 16, v0
	v_and_b32_e32 v59, 0xffff0000, v0
	v_lshlrev_b32_e32 v56, 16, v1
	v_and_b32_e32 v57, 0xffff0000, v1
	v_lshlrev_b32_e32 v54, 16, v2
	v_and_b32_e32 v55, 0xffff0000, v2
	v_lshlrev_b32_e32 v52, 16, v3
	v_and_b32_e32 v53, 0xffff0000, v3
	v_lshlrev_b32_e32 v50, 16, v4
	v_and_b32_e32 v51, 0xffff0000, v4
	v_lshlrev_b32_e32 v48, 16, v5
	v_and_b32_e32 v49, 0xffff0000, v5
	v_lshlrev_b32_e32 v46, 16, v6
	v_and_b32_e32 v47, 0xffff0000, v6
	v_lshlrev_b32_e32 v30, 16, v7
	v_lshlrev_b32_e32 v24, 16, v8
	v_and_b32_e32 v25, 0xffff0000, v8
	v_lshlrev_b32_e32 v22, 16, v9
	v_and_b32_e32 v23, 0xffff0000, v9
	v_lshlrev_b32_e32 v20, 16, v10
	v_and_b32_e32 v21, 0xffff0000, v10
	v_lshlrev_b32_e32 v16, 16, v11
	v_and_b32_e32 v17, 0xffff0000, v11
	v_lshlrev_b32_e32 v14, 16, v26
	v_and_b32_e32 v15, 0xffff0000, v26
	v_lshlrev_b32_e32 v10, 16, v27
	v_and_b32_e32 v11, 0xffff0000, v27
	v_lshlrev_b32_e32 v8, 16, v28
	v_and_b32_e32 v9, 0xffff0000, v28
	v_lshlrev_b32_e32 v28, 16, v29
	v_and_b32_e32 v27, 0xffff0000, v7
	v_and_b32_e32 v26, 0xffff0000, v29
	s_cbranch_vccnz .LBB0_200
	global_load_dwordx4 v[4:7], v[18:19], off offset:48
	global_load_dwordx4 v[42:45], v[18:19], off offset:32
	global_load_dwordx4 v[38:41], v[18:19], off offset:16
	global_load_dwordx4 v[34:37], v[18:19], off
	global_load_dwordx4 v[0:3], v[18:19], off offset:176
	global_load_dwordx4 v[66:69], v[18:19], off offset:160
	global_load_dwordx4 v[70:73], v[18:19], off offset:144
	global_load_dwordx4 v[74:77], v[18:19], off offset:128
	v_mov_b32_e32 v29, v26
	v_mov_b32_e32 v31, v27
	s_waitcnt vmcnt(0)
	v_pk_mul_f32 v[32:33], v[74:75], v[24:25]
	s_nop 0
	v_pk_fma_f32 v[32:33], v[34:35], v[58:59], v[32:33] neg_lo:[0,0,1] neg_hi:[0,0,1]
	v_pk_mul_f32 v[58:59], v[74:75], v[58:59]
	s_nop 0
	v_pk_fma_f32 v[24:25], v[34:35], v[24:25], v[58:59]
	v_pk_mul_f32 v[34:35], v[76:77], v[22:23]
	v_mov_b32_e32 v58, v32
	v_pk_fma_f32 v[34:35], v[36:37], v[56:57], v[34:35] neg_lo:[0,0,1] neg_hi:[0,0,1]
	v_pk_mul_f32 v[56:57], v[76:77], v[56:57]
	v_mov_b32_e32 v59, v33
	v_pk_fma_f32 v[22:23], v[36:37], v[22:23], v[56:57]
	v_pk_mul_f32 v[36:37], v[70:71], v[20:21]
	v_mov_b32_e32 v56, v34
	v_pk_fma_f32 v[36:37], v[38:39], v[54:55], v[36:37] neg_lo:[0,0,1] neg_hi:[0,0,1]
	v_pk_mul_f32 v[54:55], v[70:71], v[54:55]
	v_mov_b32_e32 v57, v35
	v_pk_fma_f32 v[20:21], v[38:39], v[20:21], v[54:55]
	v_pk_mul_f32 v[38:39], v[72:73], v[16:17]
	v_mov_b32_e32 v54, v36
	v_pk_fma_f32 v[38:39], v[40:41], v[52:53], v[38:39] neg_lo:[0,0,1] neg_hi:[0,0,1]
	v_pk_mul_f32 v[52:53], v[72:73], v[52:53]
	v_mov_b32_e32 v55, v37
	v_pk_fma_f32 v[16:17], v[40:41], v[16:17], v[52:53]
	v_pk_mul_f32 v[40:41], v[66:67], v[14:15]
	v_mov_b32_e32 v52, v38
	v_pk_fma_f32 v[40:41], v[42:43], v[50:51], v[40:41] neg_lo:[0,0,1] neg_hi:[0,0,1]
	v_pk_mul_f32 v[50:51], v[66:67], v[50:51]
	v_mov_b32_e32 v53, v39
	v_pk_fma_f32 v[14:15], v[42:43], v[14:15], v[50:51]
	v_pk_mul_f32 v[42:43], v[68:69], v[10:11]
	v_mov_b32_e32 v50, v40
	v_pk_fma_f32 v[42:43], v[44:45], v[48:49], v[42:43] neg_lo:[0,0,1] neg_hi:[0,0,1]
	v_pk_mul_f32 v[48:49], v[68:69], v[48:49]
	v_mov_b32_e32 v51, v41
	v_pk_fma_f32 v[10:11], v[44:45], v[10:11], v[48:49]
	v_pk_mul_f32 v[44:45], v[0:1], v[8:9]
	v_pk_mul_f32 v[0:1], v[0:1], v[46:47]
	v_pk_fma_f32 v[44:45], v[4:5], v[46:47], v[44:45] neg_lo:[0,0,1] neg_hi:[0,0,1]
	v_pk_fma_f32 v[8:9], v[4:5], v[8:9], v[0:1]
	v_pk_mul_f32 v[0:1], v[2:3], v[28:29]
	v_mul_f32_e32 v4, v2, v30
	v_mov_b32_e32 v2, v7
	v_pk_mul_f32 v[2:3], v[2:3], v[26:27]
	v_pk_fma_f32 v[0:1], v[6:7], v[30:31], v[0:1] neg_lo:[0,0,1] neg_hi:[0,0,1]
	v_mul_f32_e32 v6, v6, v28
	v_mov_b32_e32 v7, v2
	v_mov_b32_e32 v5, v3
	v_pk_add_f32 v[28:29], v[6:7], v[4:5]
	v_mov_b32_e32 v48, v42
	v_mov_b32_e32 v49, v43
	v_mov_b32_e32 v46, v44
	v_mov_b32_e32 v47, v45
	v_mov_b32_e32 v30, v0
	v_mov_b32_e32 v27, v1
	v_mov_b32_e32 v26, v29

.LBB0_222:
	s_and_b64 vcc, exec, s[0:1]
	s_cbranch_vccz .LBB0_251
	v_readfirstlane_b32 s0, v193
	s_and_b32 s0, s0, 0xffffff00
	v_readlane_b32 s1, v254, 13
	s_waitcnt vmcnt(0)
	v_mov_b32_e32 v0, v218
	s_add_i32 s0, s0, s1
	s_nop 0
	v_add_u32_e32 v0, s0, v0
	s_mov_b32 s0, 0x40000
	v_cmp_gt_i32_e32 vcc, s0, v0
	s_mov_b64 s[0:1], exec
	v_readlane_b32 s40, v253, 48
	s_nop 1
	v_readlane_b32 s48, v253, 16
	s_and_b64 s[22:23], s[0:1], vcc
	v_readlane_b32 s41, v253, 49
	v_readlane_b32 s56, v253, 24
	v_readlane_b32 s57, v253, 25
	v_readlane_b32 s58, v253, 26
	v_readlane_b32 s59, v253, 27
	v_readlane_b32 s62, v253, 30
	v_readlane_b32 s63, v253, 31
	s_mov_b32 s4, 0x3f2aaaab
	s_mov_b32 s5, 0x3f317218
	s_mov_b32 s6, 0x33800000
	s_mov_b32 s7, 0x3fb8aa3b
	s_mov_b32 s8, 0xc2ce8ed0
	s_mov_b32 s9, 0x42b17218
	v_readlane_b32 s42, v253, 50
	v_readlane_b32 s43, v253, 51
	v_readlane_b32 s44, v253, 52
	v_readlane_b32 s45, v253, 53
	v_readlane_b32 s46, v253, 54
	v_readlane_b32 s47, v253, 55
	v_readlane_b32 s49, v253, 17
	s_nop 1
	v_readlane_b32 s53, v253, 21
	v_readlane_b32 s54, v253, 22
	v_readlane_b32 s55, v253, 23
	s_nop 1
	s_mov_b64 exec, s[22:23]
	s_cbranch_execz .LBB0_226
	v_readlane_b32 s10, v254, 0
	v_readlane_b32 s11, v254, 1
	s_load_dword s22, s[10:11], 0x0
	s_lshl_b32 s20, s92, 3
	s_mov_b64 s[36:37], 0
	s_waitcnt lgkmcnt(0)
	s_lshl_b32 s22, s22, 9

.LBB0_253:
	s_waitcnt lgkmcnt(0)
	s_add_i32 s0, s0, s90
	s_cmp_ge_i32 s96, s0
	v_readfirstlane_b32 s20, v193
	s_waitcnt vmcnt(0)
	s_barrier
	s_cbranch_scc1 .LBB0_272
	v_readfirstlane_b32 s1, v193
	s_lshr_b32 s1, s1, 8
	v_readlane_b32 s4, v254, 11
	s_add_i32 s22, s1, s4
	s_cmp_ge_i32 s22, s56
	s_cbranch_scc1 .LBB0_272
	v_writelane_b32 v255, s84, 43
	s_nop 1
	s_lshl_b32 s66, s0, 1
	v_writelane_b32 v255, s85, 44
	v_writelane_b32 v255, s86, 45
	s_lshr_b32 s20, s20, 8
	s_mul_i32 s26, s92, 0xc00
	s_lshl_b32 s57, s92, 3
	v_readlane_b32 s38, v253, 50
	v_readlane_b32 s4, v253, 16
	v_writelane_b32 v255, s87, 46
	s_mul_hi_i32 s23, s92, 0xc00
	v_readlane_b32 s39, v253, 51
	s_nop 1
	s_add_u32 s28, s38, s26
	s_addc_u32 s29, s39, s23
	s_lshl_b32 s23, s1, 3
	v_readlane_b32 s6, v255, 19
	s_add_i32 s71, s6, s23
	s_lshl_b32 s23, s1, 5
	v_readlane_b32 s6, v255, 20
	s_add_i32 s70, s6, s23
	s_lshl_b32 s1, s1, 7
	v_readlane_b32 s6, v255, 21
	s_ashr_i32 s23, s22, 31
	v_readlane_b32 s18, v253, 30
	s_lshl_b32 s82, s0, 4
	s_lshl_b32 s83, s0, 6
	s_add_i32 s33, s6, s1
	s_lshl_b32 s84, s0, 8
	s_lshl_b64 s[0:1], s[22:23], 15
	v_readlane_b32 s19, v253, 31
	s_add_u32 s30, s18, s0
	s_addc_u32 s31, s19, s1
	s_ashr_i32 s67, s66, 31
	s_mul_i32 s20, s20, 0x11c00
	v_readlane_b32 s5, v253, 17
	s_lshl_b64 s[34:35], s[66:67], 15
	v_readlane_b32 s37, v253, 49
	v_readlane_b32 s40, v253, 52
	v_readlane_b32 s41, v253, 53
	v_readlane_b32 s42, v253, 54
	v_readlane_b32 s43, v253, 55
	v_readlane_b32 s44, v253, 56
	v_readlane_b32 s45, v253, 57
	v_readlane_b32 s46, v253, 58
	v_readlane_b32 s47, v253, 59
	v_readlane_b32 s48, v253, 60
	v_readlane_b32 s49, v253, 61
	s_nop 1
	s_branch .LBB0_258

.LBB0_263:
	s_or_b64 exec, exec, s[0:1]
	v_lshlrev_b32_e32 v28, 2, v32
	global_load_dwordx4 v[34:37], v28, s[28:29] offset:1024
	global_load_dwordx4 v[46:49], v28, s[28:29] offset:1040
	global_load_dwordx4 v[50:53], v28, s[28:29]
	global_load_dwordx4 v[54:57], v28, s[28:29] offset:16
	global_load_dwordx4 v[58:61], v28, s[28:29] offset:2048
	global_load_dwordx4 v[62:65], v28, s[28:29] offset:2064
	v_lshrrev_b32_e32 v32, 6, v32
	s_waitcnt vmcnt(7)
	v_and_b32_e32 v39, 0xffff0000, v3
	s_waitcnt vmcnt(6)
	v_and_b32_e32 v44, 0xffff0000, v7
	v_lshlrev_b32_e64 v32, v32, 2
	v_mul_f32_e32 v39, v39, v44
	v_lshrrev_b32_e32 v44, 1, v32
	v_add_u32_e32 v30, v30, v32
	v_sub_u32_e32 v31, v31, v44
	v_subrev_u32_e32 v30, s23, v30
	v_add_u32_e32 v74, s71, v31
	v_sub_u32_e32 v30, v30, v44
	v_add_u32_e32 v75, -1, v74
	v_add3_u32 v30, s71, v30, -1
	v_min_i32_e32 v76, s26, v30
	v_max_i32_e32 v30, 0, v75
	v_sub_u32_e32 v30, v76, v30
	v_cvt_f32_i32_e32 v30, v30
	v_and_b32_e32 v68, 0xffff0000, v4
	v_lshlrev_b32_e32 v4, 16, v4
	v_and_b32_e32 v71, 0xffff0000, v0
	v_div_scale_f32 v31, s[0:1], v30, v30, 1.0
	v_rcp_f32_e32 v32, v31
	v_lshlrev_b32_e32 v0, 16, v0
	v_mul_f32_e32 v0, v0, v4
	v_div_scale_f32 v4, vcc, 1.0, v30, 1.0
	v_fma_f32 v44, -v31, v32, 1.0
	v_fmac_f32_e32 v32, v44, v32
	v_lshlrev_b32_e32 v7, 16, v7
	v_and_b32_e32 v66, 0xffff0000, v6
	v_lshlrev_b32_e32 v3, 16, v3
	v_and_b32_e32 v69, 0xffff0000, v2
	v_mul_f32_e32 v44, v4, v32
	v_mul_f32_e32 v3, v3, v7
	v_mul_f32_e32 v7, v69, v66
	v_fma_f32 v66, -v31, v44, v4
	v_fmac_f32_e32 v44, v66, v32
	v_lshlrev_b32_e32 v6, 16, v6
	v_and_b32_e32 v67, 0xffff0000, v5
	v_lshlrev_b32_e32 v5, 16, v5
	v_lshlrev_b32_e32 v2, 16, v2
	v_and_b32_e32 v70, 0xffff0000, v1
	v_lshlrev_b32_e32 v1, 16, v1
	v_fma_f32 v4, -v31, v44, v4
	v_mul_f32_e32 v2, v2, v6
	v_mul_f32_e32 v6, v70, v67
	v_mul_f32_e32 v1, v1, v5
	v_mul_f32_e32 v5, v71, v68
	v_div_fmas_f32 v4, v4, v32, v44
	v_div_fixup_f32 v44, v4, v30, 1.0
	s_lshl_b32 s0, s23, 12
	v_lshlrev_b32_e32 v28, 16, v8
	v_and_b32_e32 v8, 0xffff0000, v8
	v_lshlrev_b32_e32 v29, 16, v9
	v_and_b32_e32 v9, 0xffff0000, v9
	s_add_u32 s0, s4, s0
	s_addc_u32 s1, s5, 0
	v_lshlrev_b32_e32 v33, 16, v10
	v_and_b32_e32 v10, 0xffff0000, v10
	v_cmp_lt_i32_e32 vcc, -1, v75
	v_lshlrev_b32_e32 v38, 16, v11
	v_and_b32_e32 v11, 0xffff0000, v11
	v_readlane_b32 s4, v253, 16
	v_readlane_b32 s8, v253, 20
	v_readlane_b32 s9, v253, 21
	v_readlane_b32 s5, v253, 17
	s_nop 1
	s_waitcnt vmcnt(5)
	v_mul_f32_e32 v0, v0, v34
	v_mul_f32_e32 v4, v5, v35
	v_mul_f32_e32 v1, v1, v36
	v_mul_f32_e32 v5, v6, v37
	s_waitcnt vmcnt(3)
	v_fmac_f32_e32 v0, v16, v50
	v_fmac_f32_e32 v4, v17, v51
	v_fmac_f32_e32 v1, v20, v52
	v_fmac_f32_e32 v5, v21, v53
	v_mul_f32_e32 v2, v2, v46
	s_waitcnt vmcnt(1)
	v_fmac_f32_e32 v0, v18, v58
	v_fmac_f32_e32 v4, v19, v59
	v_fmac_f32_e32 v1, v26, v60
	v_fmac_f32_e32 v5, v27, v61
	v_mul_f32_e32 v6, v7, v47
	v_fmac_f32_e32 v2, v14, v54
	v_mul_f32_e32 v0, v0, v28
	v_mul_f32_e32 v4, v4, v8
	v_mul_f32_e32 v1, v1, v29
	v_mul_f32_e32 v5, v5, v9
	v_fmac_f32_e32 v6, v15, v55
	v_mul_f32_e32 v3, v3, v48
	v_mul_f32_e32 v7, v39, v49
	s_waitcnt vmcnt(0)
	v_fmac_f32_e32 v2, v24, v62
	v_fmac_f32_e32 v6, v25, v63
	v_fmac_f32_e32 v3, v12, v56
	v_fmac_f32_e32 v7, v13, v57
	v_cvt_pk_bf16_f32 v0, v0, v4
	v_cvt_pk_bf16_f32 v1, v1, v5
	v_lshl_add_u64 v[4:5], s[0:1], 0, v[184:185]
	v_cmp_gt_i32_e64 s[0:1], s26, v75
	v_mul_f32_e32 v2, v2, v33
	v_mul_f32_e32 v6, v6, v10
	v_fmac_f32_e32 v3, v22, v64
	v_fmac_f32_e32 v7, v23, v65
	s_and_b64 s[64:65], vcc, s[0:1]
	v_cmp_lt_i32_e32 vcc, -2, v75
	v_cmp_lt_i32_e64 s[0:1], v74, v76
	v_mul_f32_e32 v3, v3, v38
	v_mul_f32_e32 v7, v7, v11
	v_cvt_pk_bf16_f32 v2, v2, v6
	v_cndmask_b32_e64 v6, v45, v75, s[64:65]
	s_and_b64 s[62:63], vcc, s[0:1]
	v_cvt_pk_bf16_f32 v3, v3, v7
	v_ashrrev_i32_e32 v7, 31, v6
	v_cndmask_b32_e64 v8, v45, v74, s[62:63]
	v_lshlrev_b64 v[6:7], 12, v[6:7]
	v_ashrrev_i32_e32 v9, 31, v8
	v_lshl_add_u64 v[6:7], v[4:5], 0, v[6:7]
	v_lshlrev_b64 v[8:9], 12, v[8:9]
	v_lshl_add_u64 v[8:9], v[4:5], 0, v[8:9]
	global_load_dwordx4 v[46:49], v[6:7], off offset:3584
	global_load_dwordx4 v[50:53], v[8:9], off offset:3584
	v_add_u32_e32 v6, 1, v74
	v_cmp_lt_i32_e32 vcc, -3, v75
	v_cmp_lt_i32_e64 s[0:1], v6, v76
	v_add_u32_e32 v8, 2, v74
	s_and_b64 s[60:61], vcc, s[0:1]
	v_cmp_lt_i32_e32 vcc, -4, v75
	v_cmp_lt_i32_e64 s[0:1], v8, v76
	v_cndmask_b32_e64 v6, v45, v6, s[60:61]
	s_and_b64 s[58:59], vcc, s[0:1]
	v_ashrrev_i32_e32 v7, 31, v6
	v_cndmask_b32_e64 v8, v45, v8, s[58:59]
	v_lshlrev_b64 v[6:7], 12, v[6:7]
	v_ashrrev_i32_e32 v9, 31, v8
	v_lshl_add_u64 v[6:7], v[4:5], 0, v[6:7]
	v_lshlrev_b64 v[8:9], 12, v[8:9]
	v_lshl_add_u64 v[8:9], v[4:5], 0, v[8:9]
	global_load_dwordx4 v[54:57], v[6:7], off offset:3584
	global_load_dwordx4 v[58:61], v[8:9], off offset:3584
	v_add_u32_e32 v6, 3, v74
	v_cmp_lt_i32_e32 vcc, -5, v75
	v_cmp_lt_i32_e64 s[0:1], v6, v76
	v_add_u32_e32 v8, 4, v74
	s_and_b64 s[0:1], vcc, s[0:1]
	v_cmp_lt_i32_e32 vcc, -6, v75
	v_cmp_lt_i32_e64 s[36:37], v8, v76
	v_cndmask_b32_e64 v6, v45, v6, s[0:1]
	s_and_b64 s[54:55], vcc, s[36:37]
	v_ashrrev_i32_e32 v7, 31, v6
	v_cndmask_b32_e64 v8, v45, v8, s[54:55]
	v_lshlrev_b64 v[6:7], 12, v[6:7]
	v_ashrrev_i32_e32 v9, 31, v8
	v_lshl_add_u64 v[6:7], v[4:5], 0, v[6:7]
	v_lshlrev_b64 v[8:9], 12, v[8:9]
	v_lshl_add_u64 v[8:9], v[4:5], 0, v[8:9]
	global_load_dwordx4 v[62:65], v[6:7], off offset:3584
	global_load_dwordx4 v[66:69], v[8:9], off offset:3584
	v_add_u32_e32 v6, 5, v74
	v_cmp_lt_i32_e32 vcc, -7, v75
	v_cmp_lt_i32_e64 s[36:37], v6, v76
	v_add_u32_e32 v8, 6, v74
	s_and_b64 s[52:53], vcc, s[36:37]
	v_cmp_lt_i32_e32 vcc, -8, v75
	v_cmp_lt_i32_e64 s[36:37], v8, v76
	v_cndmask_b32_e64 v6, v45, v6, s[52:53]
	s_and_b64 s[50:51], vcc, s[36:37]
	v_ashrrev_i32_e32 v7, 31, v6
	v_cndmask_b32_e64 v8, v45, v8, s[50:51]
	v_lshlrev_b64 v[6:7], 12, v[6:7]
	v_ashrrev_i32_e32 v9, 31, v8
	v_lshl_add_u64 v[6:7], v[4:5], 0, v[6:7]
	v_lshlrev_b64 v[8:9], 12, v[8:9]
	v_lshl_add_u64 v[8:9], v[4:5], 0, v[8:9]
	global_load_dwordx4 v[70:73], v[6:7], off offset:3584
	global_load_dwordx4 v[36:39], v[8:9], off offset:3584
	v_add_u32_e32 v6, 7, v74
	v_cmp_lt_i32_e32 vcc, -9, v75
	v_cmp_lt_i32_e64 s[36:37], v6, v76
	v_add_u32_e32 v8, 8, v74
	s_and_b64 s[48:49], vcc, s[36:37]
	v_cmp_lt_i32_e32 vcc, -10, v75
	v_cmp_lt_i32_e64 s[36:37], v8, v76
	v_cndmask_b32_e64 v6, v45, v6, s[48:49]
	s_and_b64 s[46:47], vcc, s[36:37]
	v_ashrrev_i32_e32 v7, 31, v6
	v_cndmask_b32_e64 v8, v45, v8, s[46:47]
	v_lshlrev_b64 v[6:7], 12, v[6:7]
	v_ashrrev_i32_e32 v9, 31, v8
	v_lshl_add_u64 v[6:7], v[4:5], 0, v[6:7]
	v_lshlrev_b64 v[8:9], 12, v[8:9]
	v_lshl_add_u64 v[8:9], v[4:5], 0, v[8:9]
	global_load_dwordx4 v[32:35], v[6:7], off offset:3584
	global_load_dwordx4 v[28:31], v[8:9], off offset:3584
	v_add_u32_e32 v6, 9, v74
	v_cmp_lt_i32_e32 vcc, -11, v75
	v_cmp_lt_i32_e64 s[36:37], v6, v76
	v_add_u32_e32 v8, 10, v74
	s_and_b64 s[44:45], vcc, s[36:37]
	v_cmp_lt_i32_e32 vcc, -12, v75
	v_cmp_lt_i32_e64 s[36:37], v8, v76
	v_cndmask_b32_e64 v6, v45, v6, s[44:45]
	s_and_b64 s[42:43], vcc, s[36:37]
	v_ashrrev_i32_e32 v7, 31, v6
	v_cndmask_b32_e64 v8, v45, v8, s[42:43]
	v_lshlrev_b64 v[6:7], 12, v[6:7]
	v_ashrrev_i32_e32 v9, 31, v8
	v_lshl_add_u64 v[6:7], v[4:5], 0, v[6:7]
	v_lshlrev_b64 v[8:9], 12, v[8:9]
	v_lshl_add_u64 v[8:9], v[4:5], 0, v[8:9]
	global_load_dwordx4 v[24:27], v[6:7], off offset:3584
	global_load_dwordx4 v[20:23], v[8:9], off offset:3584
	v_add_u32_e32 v6, 11, v74
	v_cmp_lt_i32_e32 vcc, -13, v75
	v_cmp_lt_i32_e64 s[36:37], v6, v76
	v_add_u32_e32 v8, 12, v74
	s_and_b64 s[40:41], vcc, s[36:37]
	v_cmp_lt_i32_e32 vcc, -14, v75
	v_cmp_lt_i32_e64 s[36:37], v8, v76
	v_cndmask_b32_e64 v6, v45, v6, s[40:41]
	s_and_b64 s[38:39], vcc, s[36:37]
	v_ashrrev_i32_e32 v7, 31, v6
	v_cndmask_b32_e64 v8, v45, v8, s[38:39]
	v_lshlrev_b64 v[6:7], 12, v[6:7]
	v_ashrrev_i32_e32 v9, 31, v8
	v_lshl_add_u64 v[6:7], v[4:5], 0, v[6:7]
	v_lshlrev_b64 v[8:9], 12, v[8:9]
	v_lshl_add_u64 v[8:9], v[4:5], 0, v[8:9]
	global_load_dwordx4 v[16:19], v[6:7], off offset:3584
	global_load_dwordx4 v[12:15], v[8:9], off offset:3584
	v_add_u32_e32 v6, 13, v74
	v_cmp_lt_i32_e32 vcc, -15, v75
	v_cmp_lt_i32_e64 s[36:37], v6, v76
	v_add_u32_e32 v8, 14, v74
	s_and_b64 s[36:37], vcc, s[36:37]
	v_cmp_lt_i32_e32 vcc, -16, v75
	v_cmp_lt_i32_e64 s[68:69], v8, v76
	s_and_b64 vcc, vcc, s[68:69]
	s_waitcnt vmcnt(13)
	v_lshlrev_b32_e32 v76, 16, v49
	v_and_b32_e32 v49, 0xffff0000, v49
	v_cndmask_b32_e64 v6, v45, v6, s[36:37]
	v_cndmask_b32_e32 v8, v45, v8, vcc
	v_lshlrev_b32_e32 v45, 16, v46
	v_and_b32_e32 v46, 0xffff0000, v46
	v_add_f32_e32 v49, 0, v49
	s_waitcnt vmcnt(12)
	v_lshlrev_b32_e32 v80, 16, v53
	v_and_b32_e32 v53, 0xffff0000, v53
	v_lshlrev_b32_e32 v74, 16, v47
	v_add_f32_e32 v45, 0, v45
	v_add_f32_e32 v46, 0, v46
	v_cndmask_b32_e64 v49, 0, v49, s[64:65]
	v_lshlrev_b32_e32 v77, 16, v50
	v_and_b32_e32 v50, 0xffff0000, v50
	v_cndmask_b32_e64 v53, 0, v53, s[62:63]
	v_and_b32_e32 v47, 0xffff0000, v47
	v_cndmask_b32_e64 v45, 0, v45, s[64:65]
	v_cndmask_b32_e64 v46, 0, v46, s[64:65]
	v_add_f32_e32 v74, 0, v74
	v_lshlrev_b32_e32 v78, 16, v51
	v_cndmask_b32_e64 v77, 0, v77, s[62:63]
	v_cndmask_b32_e64 v50, 0, v50, s[62:63]
	v_add_f32_e32 v49, v49, v53
	s_waitcnt vmcnt(11)
	v_lshlrev_b32_e32 v53, 16, v54
	v_lshlrev_b32_e32 v75, 16, v48
	v_cndmask_b32_e64 v74, 0, v74, s[64:65]
	v_add_f32_e32 v47, 0, v47
	v_and_b32_e32 v51, 0xffff0000, v51
	v_add_f32_e32 v45, v45, v77
	v_add_f32_e32 v46, v46, v50
	v_cndmask_b32_e64 v50, 0, v78, s[62:63]
	v_and_b32_e32 v54, 0xffff0000, v54
	v_cndmask_b32_e64 v53, 0, v53, s[60:61]
	v_and_b32_e32 v48, 0xffff0000, v48
	v_cndmask_b32_e64 v47, 0, v47, s[64:65]
	v_add_f32_e32 v75, 0, v75
	v_lshlrev_b32_e32 v79, 16, v52
	v_add_f32_e32 v50, v74, v50
	v_cndmask_b32_e64 v51, 0, v51, s[62:63]
	v_lshlrev_b32_e32 v74, 16, v55
	v_add_f32_e32 v45, v45, v53
	v_cndmask_b32_e64 v53, 0, v54, s[60:61]
	v_cndmask_b32_e64 v75, 0, v75, s[64:65]
	v_add_f32_e32 v48, 0, v48
	v_and_b32_e32 v52, 0xffff0000, v52
	v_add_f32_e32 v47, v47, v51
	v_cndmask_b32_e64 v51, 0, v79, s[62:63]
	v_and_b32_e32 v55, 0xffff0000, v55
	v_add_f32_e32 v46, v46, v53
	v_cndmask_b32_e64 v53, 0, v74, s[60:61]
	v_cndmask_b32_e64 v48, 0, v48, s[64:65]
	v_add_f32_e32 v76, 0, v76
	v_add_f32_e32 v51, v75, v51
	v_cndmask_b32_e64 v52, 0, v52, s[62:63]
	v_lshlrev_b32_e32 v75, 16, v56
	v_add_f32_e32 v50, v50, v53
	v_cndmask_b32_e64 v53, 0, v55, s[60:61]
	v_cndmask_b32_e64 v76, 0, v76, s[64:65]
	v_add_f32_e32 v48, v48, v52
	v_cndmask_b32_e64 v52, 0, v80, s[62:63]
	v_and_b32_e32 v56, 0xffff0000, v56
	v_add_f32_e32 v47, v47, v53
	v_cndmask_b32_e64 v53, 0, v75, s[60:61]
	v_add_f32_e32 v52, v76, v52
	v_lshlrev_b32_e32 v76, 16, v57
	v_add_f32_e32 v51, v51, v53
	v_cndmask_b32_e64 v53, 0, v56, s[60:61]
	v_and_b32_e32 v57, 0xffff0000, v57
	v_add_f32_e32 v48, v48, v53
	v_cndmask_b32_e64 v53, 0, v76, s[60:61]
	v_add_f32_e32 v52, v52, v53
	v_cndmask_b32_e64 v53, 0, v57, s[60:61]
	v_add_f32_e32 v49, v49, v53
	s_waitcnt vmcnt(10)
	v_lshlrev_b32_e32 v53, 16, v58
	v_and_b32_e32 v54, 0xffff0000, v58
	v_cndmask_b32_e64 v53, 0, v53, s[58:59]
	v_lshlrev_b32_e32 v55, 16, v59
	v_add_f32_e32 v45, v45, v53
	v_cndmask_b32_e64 v53, 0, v54, s[58:59]
	v_and_b32_e32 v56, 0xffff0000, v59
	v_add_f32_e32 v46, v46, v53
	v_cndmask_b32_e64 v53, 0, v55, s[58:59]
	v_lshlrev_b32_e32 v57, 16, v60
	v_add_f32_e32 v50, v50, v53
	v_cndmask_b32_e64 v53, 0, v56, s[58:59]
	v_and_b32_e32 v58, 0xffff0000, v60
	v_add_f32_e32 v47, v47, v53
	v_cndmask_b32_e64 v53, 0, v57, s[58:59]
	v_lshlrev_b32_e32 v59, 16, v61
	v_add_f32_e32 v51, v51, v53
	v_cndmask_b32_e64 v53, 0, v58, s[58:59]
	v_and_b32_e32 v60, 0xffff0000, v61
	v_add_f32_e32 v48, v48, v53
	v_cndmask_b32_e64 v53, 0, v59, s[58:59]
	v_add_f32_e32 v52, v52, v53
	v_cndmask_b32_e64 v53, 0, v60, s[58:59]
	v_add_f32_e32 v49, v49, v53
	s_waitcnt vmcnt(9)
	v_lshlrev_b32_e32 v53, 16, v62
	v_and_b32_e32 v54, 0xffff0000, v62
	v_cndmask_b32_e64 v53, 0, v53, s[0:1]
	v_lshlrev_b32_e32 v55, 16, v63
	v_add_f32_e32 v45, v45, v53
	v_cndmask_b32_e64 v53, 0, v54, s[0:1]
	v_and_b32_e32 v56, 0xffff0000, v63
	v_add_f32_e32 v46, v46, v53
	v_cndmask_b32_e64 v53, 0, v55, s[0:1]
	v_lshlrev_b32_e32 v57, 16, v64
	v_add_f32_e32 v50, v50, v53
	v_cndmask_b32_e64 v53, 0, v56, s[0:1]
	v_and_b32_e32 v58, 0xffff0000, v64
	v_add_f32_e32 v47, v47, v53
	v_cndmask_b32_e64 v53, 0, v57, s[0:1]
	v_lshlrev_b32_e32 v59, 16, v65
	v_add_f32_e32 v51, v51, v53
	v_cndmask_b32_e64 v53, 0, v58, s[0:1]
	v_and_b32_e32 v60, 0xffff0000, v65
	v_add_f32_e32 v48, v48, v53
	v_cndmask_b32_e64 v53, 0, v59, s[0:1]
	v_add_f32_e32 v52, v52, v53
	v_cndmask_b32_e64 v53, 0, v60, s[0:1]
	v_add_f32_e32 v49, v49, v53
	s_waitcnt vmcnt(8)
	v_lshlrev_b32_e32 v53, 16, v66
	v_and_b32_e32 v54, 0xffff0000, v66
	v_cndmask_b32_e64 v53, 0, v53, s[54:55]
	v_lshlrev_b32_e32 v55, 16, v67
	v_add_f32_e32 v45, v45, v53
	v_cndmask_b32_e64 v53, 0, v54, s[54:55]
	v_and_b32_e32 v56, 0xffff0000, v67
	v_add_f32_e32 v46, v46, v53
	v_cndmask_b32_e64 v53, 0, v55, s[54:55]
	v_lshlrev_b32_e32 v57, 16, v68
	v_add_f32_e32 v50, v50, v53
	v_cndmask_b32_e64 v53, 0, v56, s[54:55]
	v_and_b32_e32 v58, 0xffff0000, v68
	v_add_f32_e32 v47, v47, v53
	v_cndmask_b32_e64 v53, 0, v57, s[54:55]
	v_lshlrev_b32_e32 v59, 16, v69
	v_add_f32_e32 v51, v51, v53
	v_cndmask_b32_e64 v53, 0, v58, s[54:55]
	v_and_b32_e32 v60, 0xffff0000, v69
	v_add_f32_e32 v48, v48, v53
	v_cndmask_b32_e64 v53, 0, v59, s[54:55]
	v_add_f32_e32 v52, v52, v53
	v_cndmask_b32_e64 v53, 0, v60, s[54:55]
	v_add_f32_e32 v49, v49, v53
	s_waitcnt vmcnt(7)
	v_lshlrev_b32_e32 v53, 16, v70
	v_and_b32_e32 v54, 0xffff0000, v70
	v_cndmask_b32_e64 v53, 0, v53, s[52:53]
	v_lshlrev_b32_e32 v55, 16, v71
	v_add_f32_e32 v45, v45, v53
	v_cndmask_b32_e64 v53, 0, v54, s[52:53]
	v_and_b32_e32 v56, 0xffff0000, v71
	v_add_f32_e32 v46, v46, v53
	v_cndmask_b32_e64 v53, 0, v55, s[52:53]
	v_lshlrev_b32_e32 v57, 16, v72
	v_add_f32_e32 v50, v50, v53
	v_cndmask_b32_e64 v53, 0, v56, s[52:53]
	v_and_b32_e32 v58, 0xffff0000, v72
	v_add_f32_e32 v47, v47, v53
	v_cndmask_b32_e64 v53, 0, v57, s[52:53]
	v_lshlrev_b32_e32 v59, 16, v73
	v_add_f32_e32 v51, v51, v53
	v_cndmask_b32_e64 v53, 0, v58, s[52:53]
	v_and_b32_e32 v60, 0xffff0000, v73
	v_add_f32_e32 v48, v48, v53
	v_cndmask_b32_e64 v53, 0, v59, s[52:53]
	v_add_f32_e32 v52, v52, v53
	v_cndmask_b32_e64 v53, 0, v60, s[52:53]
	v_add_f32_e32 v49, v49, v53
	s_waitcnt vmcnt(6)
	v_lshlrev_b32_e32 v53, 16, v36
	v_and_b32_e32 v36, 0xffff0000, v36
	v_lshlrev_b32_e32 v56, 16, v39
	v_and_b32_e32 v39, 0xffff0000, v39
	v_lshlrev_b32_e32 v54, 16, v37
	v_and_b32_e32 v37, 0xffff0000, v37
	v_cndmask_b32_e64 v36, 0, v36, s[50:51]
	v_cndmask_b32_e64 v39, 0, v39, s[50:51]
	v_lshlrev_b32_e32 v55, 16, v38
	v_and_b32_e32 v38, 0xffff0000, v38
	v_add_f32_e32 v36, v46, v36
	v_cndmask_b32_e64 v46, 0, v54, s[50:51]
	v_cndmask_b32_e64 v37, 0, v37, s[50:51]
	v_add_f32_e32 v39, v49, v39
	s_waitcnt vmcnt(5)
	v_lshlrev_b32_e32 v49, 16, v32
	v_and_b32_e32 v32, 0xffff0000, v32
	v_add_f32_e32 v46, v50, v46
	v_add_f32_e32 v37, v47, v37
	v_cndmask_b32_e64 v47, 0, v55, s[50:51]
	v_cndmask_b32_e64 v38, 0, v38, s[50:51]
	v_lshlrev_b32_e32 v50, 16, v33
	v_and_b32_e32 v33, 0xffff0000, v33
	v_cndmask_b32_e64 v32, 0, v32, s[48:49]
	v_add_f32_e32 v47, v51, v47
	v_add_f32_e32 v38, v48, v38
	v_cndmask_b32_e64 v48, 0, v56, s[50:51]
	v_lshlrev_b32_e32 v51, 16, v34
	v_and_b32_e32 v34, 0xffff0000, v34
	v_add_f32_e32 v32, v36, v32
	v_cndmask_b32_e64 v36, 0, v50, s[48:49]
	v_cndmask_b32_e64 v33, 0, v33, s[48:49]
	v_add_f32_e32 v48, v52, v48
	v_lshlrev_b32_e32 v52, 16, v35
	v_and_b32_e32 v35, 0xffff0000, v35
	v_add_f32_e32 v36, v46, v36
	v_add_f32_e32 v33, v37, v33
	v_cndmask_b32_e64 v37, 0, v51, s[48:49]
	v_cndmask_b32_e64 v34, 0, v34, s[48:49]
	s_waitcnt vmcnt(4)
	v_lshlrev_b32_e32 v46, 16, v29
	v_and_b32_e32 v29, 0xffff0000, v29
	v_add_f32_e32 v37, v47, v37
	v_add_f32_e32 v34, v38, v34
	v_cndmask_b32_e64 v38, 0, v52, s[48:49]
	v_cndmask_b32_e64 v35, 0, v35, s[48:49]
	v_lshlrev_b32_e32 v47, 16, v30
	v_and_b32_e32 v30, 0xffff0000, v30
	v_cndmask_b32_e64 v29, 0, v29, s[46:47]
	v_add_f32_e32 v38, v48, v38
	v_add_f32_e32 v35, v39, v35
	v_lshlrev_b32_e32 v39, 16, v28
	v_and_b32_e32 v28, 0xffff0000, v28
	v_lshlrev_b32_e32 v48, 16, v31
	v_and_b32_e32 v31, 0xffff0000, v31
	v_add_f32_e32 v29, v33, v29
	v_cndmask_b32_e64 v33, 0, v47, s[46:47]
	v_cndmask_b32_e64 v30, 0, v30, s[46:47]
	v_cndmask_b32_e64 v28, 0, v28, s[46:47]
	v_add_f32_e32 v33, v37, v33
	v_add_f32_e32 v30, v34, v30
	v_cndmask_b32_e64 v34, 0, v48, s[46:47]
	v_cndmask_b32_e64 v31, 0, v31, s[46:47]
	s_waitcnt vmcnt(3)
	v_lshlrev_b32_e32 v37, 16, v26
	v_and_b32_e32 v26, 0xffff0000, v26
	v_ashrrev_i32_e32 v7, 31, v6
	v_ashrrev_i32_e32 v9, 31, v8
	v_add_f32_e32 v28, v32, v28
	v_cndmask_b32_e64 v32, 0, v46, s[46:47]
	v_add_f32_e32 v34, v38, v34
	v_add_f32_e32 v31, v35, v31
	v_lshlrev_b32_e32 v35, 16, v24
	v_and_b32_e32 v24, 0xffff0000, v24
	v_lshlrev_b32_e32 v38, 16, v27
	v_and_b32_e32 v27, 0xffff0000, v27
	v_cndmask_b32_e64 v26, 0, v26, s[44:45]
	v_lshlrev_b64 v[6:7], 12, v[6:7]
	v_lshlrev_b64 v[8:9], 12, v[8:9]
	v_add_f32_e32 v32, v36, v32
	v_lshlrev_b32_e32 v36, 16, v25
	v_and_b32_e32 v25, 0xffff0000, v25
	v_cndmask_b32_e64 v24, 0, v24, s[44:45]
	v_add_f32_e32 v26, v30, v26
	v_cndmask_b32_e64 v30, 0, v38, s[44:45]
	v_cndmask_b32_e64 v27, 0, v27, s[44:45]
	v_lshl_add_u64 v[6:7], v[4:5], 0, v[6:7]
	v_lshl_add_u64 v[4:5], v[4:5], 0, v[8:9]
	v_cndmask_b32_e64 v53, 0, v53, s[50:51]
	v_add_f32_e32 v24, v28, v24
	v_cndmask_b32_e64 v28, 0, v36, s[44:45]
	v_cndmask_b32_e64 v25, 0, v25, s[44:45]
	v_add_f32_e32 v30, v34, v30
	v_add_f32_e32 v27, v31, v27
	s_waitcnt vmcnt(2)
	v_lshlrev_b32_e32 v31, 16, v20
	v_and_b32_e32 v20, 0xffff0000, v20
	v_lshlrev_b32_e32 v34, 16, v23
	v_and_b32_e32 v23, 0xffff0000, v23
	global_load_dwordx4 v[8:11], v[6:7], off offset:3584
	s_nop 0
	global_load_dwordx4 v[4:7], v[4:5], off offset:3584
	v_add_f32_e32 v45, v45, v53
	v_cndmask_b32_e64 v49, 0, v49, s[48:49]
	v_add_f32_e32 v28, v32, v28
	v_add_f32_e32 v25, v29, v25
	v_cndmask_b32_e64 v29, 0, v37, s[44:45]
	v_lshlrev_b32_e32 v32, 16, v21
	v_cndmask_b32_e64 v20, 0, v20, s[42:43]
	v_cndmask_b32_e64 v23, 0, v23, s[42:43]
	v_add_f32_e32 v45, v45, v49
	v_cndmask_b32_e64 v39, 0, v39, s[46:47]
	v_add_f32_e32 v29, v33, v29
	v_and_b32_e32 v21, 0xffff0000, v21
	v_lshlrev_b32_e32 v33, 16, v22
	v_and_b32_e32 v22, 0xffff0000, v22
	v_add_f32_e32 v20, v24, v20
	v_cndmask_b32_e64 v24, 0, v32, s[42:43]
	v_add_f32_e32 v23, v27, v23
	s_waitcnt vmcnt(3)
	v_lshlrev_b32_e32 v27, 16, v16
	v_and_b32_e32 v16, 0xffff0000, v16
	v_add_f32_e32 v39, v45, v39
	v_cndmask_b32_e64 v35, 0, v35, s[44:45]
	v_add_f32_e32 v24, v28, v24
	v_cndmask_b32_e64 v21, 0, v21, s[42:43]
	v_cndmask_b32_e64 v22, 0, v22, s[42:43]
	v_lshlrev_b32_e32 v28, 16, v17
	v_cndmask_b32_e64 v16, 0, v16, s[40:41]
	v_add_f32_e32 v35, v39, v35
	v_cndmask_b32_e64 v31, 0, v31, s[42:43]
	v_add_f32_e32 v21, v25, v21
	v_cndmask_b32_e64 v25, 0, v33, s[42:43]
	v_add_f32_e32 v22, v26, v22
	v_cndmask_b32_e64 v26, 0, v34, s[42:43]
	v_and_b32_e32 v17, 0xffff0000, v17
	v_add_f32_e32 v20, v20, v16
	v_cndmask_b32_e64 v16, 0, v28, s[40:41]
	v_add_f32_e32 v31, v35, v31
	v_add_f32_e32 v25, v29, v25
	v_add_f32_e32 v26, v30, v26
	v_lshlrev_b32_e32 v29, 16, v18
	v_and_b32_e32 v30, 0xffff0000, v18
	v_cndmask_b32_e64 v18, 0, v27, s[40:41]
	v_add_f32_e32 v24, v24, v16
	v_cndmask_b32_e64 v16, 0, v17, s[40:41]
	v_lshlrev_b32_e32 v32, 16, v19
	v_and_b32_e32 v33, 0xffff0000, v19
	v_add_f32_e32 v27, v31, v18
	v_add_f32_e32 v21, v21, v16
	global_load_dwordx4 v[16:19], v[42:43], off offset:3584
	v_cndmask_b32_e64 v28, 0, v29, s[40:41]
	v_add_f32_e32 v25, v25, v28
	v_cndmask_b32_e64 v28, 0, v30, s[40:41]
	v_add_f32_e32 v22, v22, v28
	v_cndmask_b32_e64 v28, 0, v32, s[40:41]
	v_add_f32_e32 v26, v26, v28
	v_cndmask_b32_e64 v28, 0, v33, s[40:41]
	v_add_f32_e32 v23, v23, v28
	s_waitcnt vmcnt(3)
	v_lshlrev_b32_e32 v28, 16, v12
	v_and_b32_e32 v12, 0xffff0000, v12
	v_lshlrev_b32_e32 v29, 16, v13
	v_and_b32_e32 v13, 0xffff0000, v13
	v_lshlrev_b32_e32 v30, 16, v14
	v_and_b32_e32 v14, 0xffff0000, v14
	v_lshlrev_b32_e32 v31, 16, v15
	v_and_b32_e32 v15, 0xffff0000, v15
	v_cndmask_b32_e64 v12, 0, v12, s[38:39]
	v_add_f32_e32 v12, v20, v12
	v_cndmask_b32_e64 v20, 0, v29, s[38:39]
	v_cndmask_b32_e64 v13, 0, v13, s[38:39]
	v_cndmask_b32_e64 v14, 0, v14, s[38:39]
	v_cndmask_b32_e64 v15, 0, v15, s[38:39]
	v_add_f32_e32 v20, v24, v20
	v_add_f32_e32 v13, v21, v13
	v_cndmask_b32_e64 v21, 0, v30, s[38:39]
	v_add_f32_e32 v14, v22, v14
	v_cndmask_b32_e64 v22, 0, v31, s[38:39]
	v_add_f32_e32 v15, v23, v15
	v_add_f32_e32 v21, v25, v21
	v_add_f32_e32 v22, v26, v22
	s_waitcnt vmcnt(2)
	v_lshlrev_b32_e32 v23, 16, v8
	v_and_b32_e32 v8, 0xffff0000, v8
	v_lshlrev_b32_e32 v24, 16, v9
	v_and_b32_e32 v9, 0xffff0000, v9
	v_lshlrev_b32_e32 v25, 16, v10
	v_and_b32_e32 v10, 0xffff0000, v10
	v_lshlrev_b32_e32 v26, 16, v11
	v_and_b32_e32 v11, 0xffff0000, v11
	v_cndmask_b32_e64 v8, 0, v8, s[36:37]
	v_cndmask_b32_e64 v9, 0, v9, s[36:37]
	v_add_f32_e32 v8, v12, v8
	v_cndmask_b32_e64 v12, 0, v24, s[36:37]
	v_add_f32_e32 v9, v13, v9
	v_cndmask_b32_e64 v13, 0, v25, s[36:37]
	v_cndmask_b32_e64 v10, 0, v10, s[36:37]
	v_cndmask_b32_e64 v11, 0, v11, s[36:37]
	v_add_f32_e32 v12, v20, v12
	v_add_f32_e32 v13, v21, v13
	v_add_f32_e32 v10, v14, v10
	v_cndmask_b32_e64 v14, 0, v26, s[36:37]
	v_add_f32_e32 v11, v15, v11
	s_waitcnt vmcnt(1)
	v_lshlrev_b32_e32 v15, 16, v4
	v_and_b32_e32 v4, 0xffff0000, v4
	v_lshlrev_b32_e32 v20, 16, v5
	v_and_b32_e32 v5, 0xffff0000, v5
	v_lshlrev_b32_e32 v21, 16, v6
	v_and_b32_e32 v6, 0xffff0000, v6
	v_add_f32_e32 v14, v22, v14
	v_lshlrev_b32_e32 v22, 16, v7
	v_cndmask_b32_e32 v4, 0, v4, vcc
	v_cndmask_b32_e32 v5, 0, v5, vcc
	v_cndmask_b32_e32 v6, 0, v6, vcc
	v_add_f32_e32 v4, v8, v4
	v_cndmask_b32_e32 v8, 0, v20, vcc
	v_add_f32_e32 v5, v9, v5
	v_cndmask_b32_e32 v9, 0, v21, vcc
	v_add_f32_e32 v6, v10, v6
	v_cndmask_b32_e32 v10, 0, v22, vcc
	v_cndmask_b32_e64 v28, 0, v28, s[38:39]
	v_add_f32_e32 v8, v12, v8
	v_add_f32_e32 v9, v13, v9
	v_add_f32_e32 v10, v14, v10
	v_add_f32_e32 v27, v27, v28
	v_cndmask_b32_e64 v23, 0, v23, s[36:37]
	v_and_b32_e32 v7, 0xffff0000, v7
	v_add_f32_e32 v23, v27, v23
	v_cndmask_b32_e32 v15, 0, v15, vcc
	v_cndmask_b32_e32 v7, 0, v7, vcc
	v_add_f32_e32 v15, v23, v15
	s_waitcnt vmcnt(0)
	v_and_b32_e32 v12, 0xffff0000, v16
	v_lshlrev_b32_e32 v13, 16, v17
	v_and_b32_e32 v14, 0xffff0000, v17
	v_fma_f32 v12, v44, v4, -v12
	v_fma_f32 v8, v44, v8, -v13
	v_fma_f32 v13, v44, v5, -v14
	v_lshlrev_b64 v[4:5], 11, v[40:41]
	v_lshl_add_u64 v[4:5], s[8:9], 0, v[4:5]
	v_add_f32_e32 v7, v11, v7
	v_lshlrev_b32_e32 v11, 16, v16
	v_lshlrev_b32_e32 v16, 16, v18
	v_and_b32_e32 v17, 0xffff0000, v18
	v_lshlrev_b32_e32 v18, 16, v19
	v_and_b32_e32 v19, 0xffff0000, v19
	v_lshl_add_u64 v[4:5], v[4:5], 0, v[184:185]
	s_mov_b64 s[0:1], 0
	s_nop 1
	v_fma_f32 v11, v44, v15, -v11
	v_fma_f32 v9, v44, v9, -v16
	v_fma_f32 v6, v44, v6, -v17
	v_fma_f32 v10, v44, v10, -v18
	v_fma_f32 v7, v44, v7, -v19
	global_store_dwordx4 v[4:5], v[0:3], off offset:512
	s_nop 1
	v_cvt_pk_bf16_f32 v0, v11, v12
	v_cvt_pk_bf16_f32 v1, v8, v13
	v_cvt_pk_bf16_f32 v2, v9, v6
	v_cvt_pk_bf16_f32 v3, v10, v7
	global_store_dwordx4 v[4:5], v[0:3], off offset:1536

.LBB0_269:
	s_and_b32 s27, s27, 3
	s_or_b32 s36, s27, s57
	v_ashrrev_i32_e32 v59, 1, v58
	s_ashr_i32 s37, s36, 31
	v_add_u32_e32 v0, s26, v59
	s_lshl_b64 s[36:37], s[36:37], 2
	v_readlane_b32 s40, v253, 48
	v_ashrrev_i32_e32 v1, 31, v0
	v_readlane_b32 s4, v253, 16
	v_readlane_b32 s41, v253, 49
	s_add_u32 s36, s40, s36
	v_lshlrev_b64 v[0:1], 12, v[0:1]
	v_readlane_b32 s5, v253, 17
	s_addc_u32 s37, s41, s37
	v_and_b32_e32 v60, 1, v58
	v_lshl_add_u64 v[0:1], s[4:5], 0, v[0:1]
	s_lshl_b32 s88, s27, 7
	v_lshl_add_u64 v[0:1], v[0:1], 0, s[88:89]
	v_lshlrev_b32_e32 v184, 6, v60
	v_lshl_add_u64 v[8:9], v[0:1], 0, v[184:185]
	global_load_dwordx4 v[0:3], v[8:9], off offset:512
	global_load_dwordx4 v[4:7], v[8:9], off offset:528
	global_load_dwordx4 v[10:13], v[8:9], off offset:544
	global_load_dwordx4 v[18:21], v[8:9], off offset:560
	global_load_dword v61, v185, s[36:37]
	global_load_dword v62, v185, s[36:37] offset:16
	v_readlane_b32 s16, v253, 28
	v_readlane_b32 s17, v253, 29
	s_andn2_b64 vcc, exec, s[0:1]
	v_readlane_b32 s42, v253, 50
	v_readlane_b32 s43, v253, 51
	v_readlane_b32 s44, v253, 52
	v_readlane_b32 s45, v253, 53
	v_readlane_b32 s46, v253, 54
	v_readlane_b32 s47, v253, 55
	v_readlane_b32 s48, v253, 56
	v_readlane_b32 s49, v253, 57
	s_nop 1
	v_readlane_b32 s53, v253, 61
	v_readlane_b32 s54, v253, 62
	v_readlane_b32 s55, v253, 63
	s_nop 1
	s_waitcnt vmcnt(5)
	v_lshlrev_b32_e32 v42, 16, v0
	v_and_b32_e32 v43, 0xffff0000, v0
	v_lshlrev_b32_e32 v40, 16, v1
	v_and_b32_e32 v41, 0xffff0000, v1
	v_lshlrev_b32_e32 v38, 16, v2
	v_and_b32_e32 v39, 0xffff0000, v2
	v_lshlrev_b32_e32 v36, 16, v3
	v_and_b32_e32 v37, 0xffff0000, v3
	s_waitcnt vmcnt(4)
	v_lshlrev_b32_e32 v34, 16, v4
	v_and_b32_e32 v35, 0xffff0000, v4
	v_lshlrev_b32_e32 v32, 16, v5
	v_and_b32_e32 v33, 0xffff0000, v5
	v_lshlrev_b32_e32 v30, 16, v6
	v_and_b32_e32 v31, 0xffff0000, v6
	v_lshlrev_b32_e32 v28, 16, v7
	s_waitcnt vmcnt(3)
	v_lshlrev_b32_e32 v26, 16, v10
	v_and_b32_e32 v27, 0xffff0000, v10
	v_lshlrev_b32_e32 v24, 16, v11
	v_and_b32_e32 v25, 0xffff0000, v11
	v_lshlrev_b32_e32 v22, 16, v12
	v_and_b32_e32 v23, 0xffff0000, v12
	v_lshlrev_b32_e32 v16, 16, v13
	v_and_b32_e32 v17, 0xffff0000, v13
	s_waitcnt vmcnt(2)
	v_lshlrev_b32_e32 v14, 16, v18
	v_and_b32_e32 v15, 0xffff0000, v18
	v_lshlrev_b32_e32 v12, 16, v19
	v_and_b32_e32 v13, 0xffff0000, v19
	v_lshlrev_b32_e32 v10, 16, v20
	v_and_b32_e32 v11, 0xffff0000, v20
	v_lshlrev_b32_e32 v20, 16, v21
	v_and_b32_e32 v19, 0xffff0000, v7
	v_and_b32_e32 v18, 0xffff0000, v21
	s_cbranch_vccnz .LBB0_256
	v_add_u32_e32 v0, s23, v59
	v_ashrrev_i32_e32 v1, 31, v0
	v_lshlrev_b64 v[0:1], 8, v[0:1]
	v_lshl_add_u64 v[0:1], s[16:17], 0, v[0:1]
	v_lshl_add_u64 v[44:45], v[0:1], 0, v[184:185]
	global_load_dwordx4 v[4:7], v[44:45], off offset:48
	global_load_dwordx4 v[54:57], v[44:45], off offset:32
	global_load_dwordx4 v[50:53], v[44:45], off offset:16
	global_load_dwordx4 v[46:49], v[44:45], off
	global_load_dwordx4 v[0:3], v[44:45], off offset:176
	global_load_dwordx4 v[64:67], v[44:45], off offset:160
	global_load_dwordx4 v[68:71], v[44:45], off offset:144
	global_load_dwordx4 v[72:75], v[44:45], off offset:128
	v_mov_b32_e32 v21, v18
	v_mov_b32_e32 v29, v19
	s_waitcnt vmcnt(0)
	v_pk_mul_f32 v[44:45], v[72:73], v[26:27]
	s_nop 0
	v_pk_fma_f32 v[44:45], v[46:47], v[42:43], v[44:45] neg_lo:[0,0,1] neg_hi:[0,0,1]
	v_pk_mul_f32 v[42:43], v[72:73], v[42:43]
	s_nop 0
	v_pk_fma_f32 v[26:27], v[46:47], v[26:27], v[42:43]
	v_pk_mul_f32 v[42:43], v[74:75], v[24:25]
	s_nop 0
	v_pk_fma_f32 v[46:47], v[48:49], v[40:41], v[42:43] neg_lo:[0,0,1] neg_hi:[0,0,1]
	v_pk_mul_f32 v[40:41], v[74:75], v[40:41]
	v_mov_b32_e32 v42, v44
	v_pk_fma_f32 v[24:25], v[48:49], v[24:25], v[40:41]
	v_pk_mul_f32 v[40:41], v[68:69], v[22:23]
	v_mov_b32_e32 v43, v45
	v_pk_fma_f32 v[48:49], v[50:51], v[38:39], v[40:41] neg_lo:[0,0,1] neg_hi:[0,0,1]
	v_pk_mul_f32 v[38:39], v[68:69], v[38:39]
	v_mov_b32_e32 v40, v46
	v_pk_fma_f32 v[22:23], v[50:51], v[22:23], v[38:39]
	v_pk_mul_f32 v[38:39], v[70:71], v[16:17]
	v_mov_b32_e32 v41, v47
	v_pk_fma_f32 v[50:51], v[52:53], v[36:37], v[38:39] neg_lo:[0,0,1] neg_hi:[0,0,1]
	v_pk_mul_f32 v[36:37], v[70:71], v[36:37]
	v_mov_b32_e32 v38, v48
	v_pk_fma_f32 v[16:17], v[52:53], v[16:17], v[36:37]
	v_pk_mul_f32 v[36:37], v[64:65], v[14:15]
	v_mov_b32_e32 v39, v49
	v_pk_fma_f32 v[52:53], v[54:55], v[34:35], v[36:37] neg_lo:[0,0,1] neg_hi:[0,0,1]
	v_pk_mul_f32 v[34:35], v[64:65], v[34:35]
	v_mov_b32_e32 v36, v50
	v_pk_fma_f32 v[14:15], v[54:55], v[14:15], v[34:35]
	v_pk_mul_f32 v[34:35], v[66:67], v[12:13]
	v_mov_b32_e32 v37, v51
	v_pk_fma_f32 v[54:55], v[56:57], v[32:33], v[34:35] neg_lo:[0,0,1] neg_hi:[0,0,1]
	v_pk_mul_f32 v[32:33], v[66:67], v[32:33]
	v_mov_b32_e32 v34, v52
	v_pk_fma_f32 v[12:13], v[56:57], v[12:13], v[32:33]
	v_pk_mul_f32 v[32:33], v[0:1], v[10:11]
	v_pk_mul_f32 v[0:1], v[0:1], v[30:31]
	v_pk_fma_f32 v[56:57], v[4:5], v[30:31], v[32:33] neg_lo:[0,0,1] neg_hi:[0,0,1]
	v_pk_fma_f32 v[10:11], v[4:5], v[10:11], v[0:1]
	v_pk_mul_f32 v[0:1], v[2:3], v[20:21]
	v_mul_f32_e32 v4, v2, v28
	v_mov_b32_e32 v2, v7
	v_pk_mul_f32 v[2:3], v[2:3], v[18:19]
	v_pk_fma_f32 v[0:1], v[6:7], v[28:29], v[0:1] neg_lo:[0,0,1] neg_hi:[0,0,1]
	v_mul_f32_e32 v6, v6, v20
	v_mov_b32_e32 v7, v2
	v_mov_b32_e32 v5, v3
	v_pk_add_f32 v[20:21], v[6:7], v[4:5]
	v_mov_b32_e32 v35, v53
	v_mov_b32_e32 v32, v54
	v_mov_b32_e32 v33, v55
	v_mov_b32_e32 v30, v56
	v_mov_b32_e32 v31, v57
	v_mov_b32_e32 v28, v0
	v_mov_b32_e32 v19, v1
	v_mov_b32_e32 v18, v21
	s_branch .LBB0_256
.LBB0_271:
	v_readlane_b32 s64, v255, 43
	v_readlane_b32 s65, v255, 44
	s_mov_b64 s[84:85], s[64:65]
	s_mov_b32 s36, 0x800000
	s_mov_b32 s70, 0xbfb8aa3b
	s_mov_b32 s71, 0x42ce8ed0
	s_nop 1

.LBB0_481:
	s_movk_i32 s50, 0x8000
	s_and_b64 vcc, exec, s[0:1]
	s_movk_i32 s55, 0x2000
	s_movk_i32 s52, 0x6000
	s_brev_b32 s53, 1
	s_movk_i32 s35, 0x6400
	s_mov_b64 s[82:83], 0x60000
	s_mov_b32 s51, -1
	s_cbranch_vccz .LBB0_622
	v_readlane_b32 s0, v254, 0
	v_readlane_b32 s1, v254, 1
	s_load_dword s0, s[0:1], 0x0
	v_readfirstlane_b32 s1, v193
	s_lshr_b32 s1, s1, 8
	v_readlane_b32 s4, v254, 11
	s_add_i32 s22, s1, s4
	s_waitcnt lgkmcnt(0)
	s_lshl_b32 s54, s0, 1
	s_waitcnt vmcnt(0)
	v_mov_b32_e32 v1, v218
	s_cmpk_gt_i32 s22, 0x107f
	s_cbranch_scc1 .LBB0_519
	v_cvt_f32_i32_e32 v7, v1
	v_readlane_b32 s36, v253, 0
	v_lshlrev_b32_e32 v6, 2, v1
	v_readlane_b32 s37, v253, 1
	v_mul_f32_e32 v7, 0x3d000000, v7
	v_mul_f32_e64 v8, |v7|, 0.5
	v_fract_f32_e32 v9, v8
	v_add_f32_e32 v9, v9, v9
	v_cmp_neq_f32_e32 vcc, s21, v8
	v_cmp_gt_f32_e64 s[0:1], |v7|, 1.0
	v_ashrrev_i32_e32 v0, 4, v1
	v_cndmask_b32_e32 v8, 0, v9, vcc
	v_cndmask_b32_e64 v8, |v7|, v8, s[0:1]
	v_add_f32_e32 v9, v8, v8
	v_rndne_f32_e32 v9, v9
	v_fmac_f32_e32 v8, -0.5, v9
	v_mul_f32_e32 v11, v8, v8
	v_fmamk_f32 v12, v11, 0x3e75aa41, v220
	v_fmaak_f32 v12, v11, v12, 0x40234736
	v_fmaak_f32 v12, v11, v12, 0xc0a55e0e
	v_mul_f32_e32 v13, v8, v11
	v_mul_f32_e32 v12, v13, v12
	v_cvt_i32_f32_e32 v10, v9
	v_fmac_f32_e32 v12, 0x40490fdb, v8
	v_fmamk_f32 v8, v11, 0x3d4be544, v221
	v_fmaak_f32 v8, v11, v8, 0xbfaad1da
	v_fmaak_f32 v8, v11, v8, 0x4081e0d3
	v_fmaak_f32 v8, v11, v8, 0xc09de9e6
	v_fma_f32 v8, v11, v8, 1.0
	v_and_b32_e32 v11, 1, v10
	v_cmp_eq_u32_e32 vcc, 0, v11
	v_and_b32_e32 v2, 60, v6
	v_and_b32_e32 v34, 63, v1
	v_ashrrev_i32_e32 v35, 2, v1
	v_cmp_gt_i32_e64 s[36:37], 64, v1
	v_and_b32_e32 v1, 0x7fffffff, v7
	v_and_b32_e32 v9, 2, v10
	v_cndmask_b32_e64 v11, -v12, v8, vcc
	v_add_u32_e32 v39, s2, v6
	v_cndmask_b32_e32 v6, v8, v12, vcc
	v_lshlrev_b32_e32 v8, 30, v10
	v_cmp_eq_u32_e64 s[0:1], 0, v9
	v_and_b32_e32 v8, 0x80000000, v8
	v_xor_b32_e32 v1, v1, v7
	v_cndmask_b32_e64 v9, -v11, v11, s[0:1]
	s_movk_i32 s0, 0x1f8
	v_xor_b32_e32 v1, v1, v8
	v_cmp_class_f32_e64 s[0:1], v7, s0
	v_xor_b32_e32 v1, v1, v6
	v_and_b32_e32 v3, -16, v35
	v_cndmask_b32_e64 v38, v236, v9, s[0:1]
	v_cndmask_b32_e64 v40, v236, v1, s[0:1]
	s_movk_i32 s0, 0x41
	s_movk_i32 s34, 0x104
	v_mad_u64_u32 v[10:11], s[0:1], v0, s0, v[2:3]
	v_mov_b32_e32 v36, s2
	v_ashrrev_i32_e32 v1, 31, v0
	v_add_u32_e32 v12, 16, v0
	v_lshlrev_b32_e32 v184, 1, v34
	v_readlane_b32 s38, v253, 2
	v_readlane_b32 s39, v253, 3
	v_readlane_b32 s40, v253, 4
	v_readlane_b32 s41, v253, 5
	s_nop 1
	v_lshl_add_u32 v41, v10, 2, s2
	v_lshlrev_b64 v[10:11], 12, v[0:1]
	v_ashrrev_i32_e32 v13, 31, v12
	v_add_u32_e32 v18, 32, v0
	v_add_u32_e32 v24, 48, v0
	s_nop 1
	v_mad_u32_u24 v1, v34, s34, v36
	v_lshrrev_b32_e32 v34, 4, v35
	s_movk_i32 s50, 0x8000
	v_lshl_add_u64 v[4:5], s[40:41], 0, v[184:185]
	v_lshl_add_u64 v[6:7], s[38:39], 0, v[184:185]
	v_lshlrev_b32_e32 v8, 6, v0
	v_lshlrev_b32_e32 v14, 6, v12
	v_lshlrev_b64 v[16:17], 12, v[12:13]
	v_lshlrev_b32_e32 v20, 6, v18
	v_ashrrev_i32_e32 v19, 31, v18
	v_lshlrev_b32_e32 v26, 6, v24
	v_ashrrev_i32_e32 v25, 31, v24
	v_lshlrev_b32_e32 v184, 2, v2
	v_readlane_b32 s60, v253, 52
	v_readlane_b32 s61, v253, 53
	v_readlane_b32 s62, v253, 54
	v_readlane_b32 s63, v253, 55
	s_nop 1
	v_lshlrev_b32_e32 v13, 6, v34
	s_add_i32 s0, s2, 0x4100
	s_mov_b32 s51, -1
	v_ashrrev_i32_e32 v9, 31, v8
	v_ashrrev_i32_e32 v15, 31, v14
	v_ashrrev_i32_e32 v21, 31, v20
	v_lshlrev_b64 v[22:23], 12, v[18:19]
	v_ashrrev_i32_e32 v27, 31, v26
	v_lshlrev_b64 v[28:29], 12, v[24:25]
	s_mov_b32 s71, 0x42ce8ed0
	s_mov_b32 s70, 0xbfb8aa3b
	v_lshl_add_u64 v[30:31], s[60:61], 0, v[184:185]
	v_lshl_add_u64 v[32:33], s[62:63], 0, v[184:185]
	v_add_u32_e32 v19, s0, v13
	v_lshlrev_b32_e32 v25, 5, v34
	v_mul_lo_u32 v42, v34, 48
	s_mov_b32 s20, s22
	v_readlane_b32 s42, v253, 6
	v_readlane_b32 s43, v253, 7
	v_readlane_b32 s44, v253, 8
	v_readlane_b32 s45, v253, 9
	v_readlane_b32 s46, v253, 10
	v_readlane_b32 s47, v253, 11
	v_readlane_b32 s48, v253, 12
	v_readlane_b32 s49, v253, 13
	s_nop 1
	v_readlane_b32 s65, v253, 57
	s_nop 1
	v_readlane_b32 s68, v253, 60
	v_readlane_b32 s69, v253, 61
	s_branch .LBB0_485

.LBB0_497:
	s_and_b64 vcc, exec, s[0:1]
	s_cbranch_vccz .LBB0_518
	s_lshl_b32 s0, s20, 6
	s_nop 1
	s_and_b32 s26, s0, 0x3c0
	s_lshl_b32 s0, s20, 2
	v_readlane_b32 s18, v253, 46
	v_readlane_b32 s19, v253, 47
	s_and_b32 s23, s0, 0x7fc0
	v_add_u32_e32 v47, s26, v0
	v_mov_b64_e32 v[34:35], s[18:19]
	s_add_i32 s88, s23, 0xffffc000
	v_mad_i64_i32 v[48:49], s[0:1], v47, s35, v[34:35]
	s_lshl_b64 s[0:1], s[88:89], 2
	s_nop 0
	v_lshl_add_u64 v[48:49], v[48:49], 0, s[0:1]
	v_lshl_add_u64 v[48:49], v[48:49], 0, v[184:185]
	v_add_co_u32_e32 v48, vcc, 0x1000, v48
	v_add_u32_e32 v47, s26, v12
	s_nop 0
	v_addc_co_u32_e32 v49, vcc, 0, v49, vcc
	global_load_dwordx4 v[48:51], v[48:49], off offset:3072
	s_movk_i32 s4, 0x1000
	s_nop 1
	s_waitcnt vmcnt(0)
	ds_write2_b32 v41, v48, v49 offset1:1
	ds_write2_b32 v41, v50, v51 offset0:2 offset1:3
	v_mad_i64_i32 v[48:49], s[28:29], v47, s35, v[34:35]
	v_lshl_add_u64 v[48:49], v[48:49], 0, s[0:1]
	v_lshl_add_u64 v[48:49], v[48:49], 0, v[184:185]
	v_add_co_u32_e32 v48, vcc, s4, v48
	s_nop 1
	v_addc_co_u32_e32 v49, vcc, 0, v49, vcc
	global_load_dwordx4 v[48:51], v[48:49], off offset:3072
	s_waitcnt vmcnt(0)
	ds_write2_b32 v45, v48, v49 offset1:1
	ds_write2_b32 v46, v50, v51 offset1:1
	v_add_u32_e32 v45, s26, v18
	v_mad_i64_i32 v[46:47], s[28:29], v45, s35, v[34:35]
	v_lshl_add_u64 v[46:47], v[46:47], 0, s[0:1]
	v_lshl_add_u64 v[46:47], v[46:47], 0, v[184:185]
	v_add_co_u32_e32 v46, vcc, s4, v46
	s_nop 1
	v_addc_co_u32_e32 v47, vcc, 0, v47, vcc
	global_load_dwordx4 v[46:49], v[46:47], off offset:3072
	s_waitcnt vmcnt(0)
	ds_write2_b32 v43, v46, v47 offset1:1
	ds_write2_b32 v44, v48, v49 offset1:1
	v_add_u32_e32 v43, s26, v24
	v_mad_i64_i32 v[34:35], s[28:29], v43, s35, v[34:35]
	v_lshl_add_u64 v[34:35], v[34:35], 0, s[0:1]
	v_lshl_add_u64 v[34:35], v[34:35], 0, v[184:185]
	v_add_co_u32_e32 v34, vcc, 0x1000, v34
	s_nop 1
	v_addc_co_u32_e32 v35, vcc, 0, v35, vcc
	global_load_dwordx4 v[44:47], v[34:35], off offset:3072
	s_waitcnt vmcnt(0)
	ds_write2_b32 v36, v44, v45 offset1:1
	ds_write2_b32 v37, v46, v47 offset1:1
	s_and_saveexec_b64 s[0:1], s[36:37]
	ds_write2st64_b32 v39, v38, v40 offset0:65 offset1:66
	s_or_b64 exec, exec, s[0:1]
	s_lshl_b32 s88, s26, 1
	s_add_i32 s0, s23, 0xffffd800
	v_lshl_add_u64 v[34:35], v[6:7], 0, s[88:89]
	s_add_i32 s1, s23, 0xffffd900
	s_mov_b32 s23, 0
	v_mov_b32_e32 v43, v42
	v_mov_b32_e32 v44, v25
	v_mov_b32_e32 v45, v13
	v_mov_b32_e32 v46, v3
	s_waitcnt lgkmcnt(0)
	s_barrier

.LBB0_506:
	s_add_i32 s0, s20, 0xf2c0
	s_and_b32 s1, s0, 0xffff
	s_mul_i32 s1, s1, 0xba2f
	s_lshr_b32 s1, s1, 21
	s_mul_i32 s23, s1, 44
	s_sub_i32 s0, s0, s23
	s_lshl_b32 s0, s0, 6
	v_mov_b32_e32 v43, v218
	s_nop 1
	s_and_b32 s0, s0, 0xffc0
	s_lshl_b32 s23, s1, 8
	v_ashrrev_i32_e32 v36, 4, v43
	v_readlane_b32 s70, v253, 62
	v_readlane_b32 s71, v253, 63
	s_add_u32 s26, s70, s23
	v_lshlrev_b32_e32 v48, 4, v43
	v_add_u32_e32 v46, s0, v36
	s_addc_u32 s27, s71, 0
	v_and_b32_e32 v184, 0xf0, v48
	v_ashrrev_i32_e32 v47, 31, v46
	v_lshl_add_u64 v[44:45], s[26:27], 0, v[184:185]
	v_lshlrev_b64 v[34:35], 12, v[46:47]
	v_lshl_add_u64 v[34:35], v[44:45], 0, v[34:35]
	v_mul_lo_u32 v36, v36, s34
	v_add3_u32 v47, s2, v36, v184
	global_load_dwordx4 v[60:63], v[34:35], off nt
	s_nop 1
	v_readlane_b32 s66, v253, 10
	v_readlane_b32 s67, v253, 11
	s_lshl_b32 s88, s0, 1
	s_nop 1
	s_mov_b32 s71, 0x42ce8ed0
	s_mov_b32 s70, 0xbfb8aa3b
	s_nop 1
	v_readlane_b32 s65, v253, 9
	v_readlane_b32 s68, v253, 12
	v_readlane_b32 s69, v253, 13
	v_add_u32_e32 v34, 16, v46
	v_ashrrev_i32_e32 v35, 31, v34
	v_lshlrev_b64 v[34:35], 12, v[34:35]
	v_lshl_add_u64 v[34:35], v[44:45], 0, v[34:35]
	global_load_dwordx4 v[64:67], v[34:35], off nt
	v_add_u32_e32 v34, 32, v46
	v_ashrrev_i32_e32 v35, 31, v34
	v_lshlrev_b64 v[34:35], 12, v[34:35]
	v_lshl_add_u64 v[34:35], v[44:45], 0, v[34:35]
	global_load_dwordx4 v[68:71], v[34:35], off nt
	v_add_u32_e32 v34, 48, v46
	v_ashrrev_i32_e32 v35, 31, v34
	v_lshlrev_b64 v[34:35], 12, v[34:35]
	v_lshl_add_u64 v[34:35], v[44:45], 0, v[34:35]
	global_load_dwordx4 v[72:75], v[34:35], off nt
	s_waitcnt vmcnt(3)
	ds_write2_b32 v47, v60, v61 offset1:1
	ds_write2_b32 v47, v62, v63 offset0:2 offset1:3
	s_waitcnt vmcnt(2)
	v_add_u32_e32 v58, 0x1040, v47
	ds_write2_b32 v58, v64, v65 offset1:1
	v_add_u32_e32 v58, 0x1048, v47
	ds_write2_b32 v58, v66, v67 offset1:1
	s_waitcnt vmcnt(1)
	v_add_u32_e32 v58, 0x2080, v47
	ds_write2_b32 v58, v68, v69 offset1:1
	v_add_u32_e32 v58, 0x2088, v47
	ds_write2_b32 v58, v70, v71 offset1:1
	s_waitcnt vmcnt(0)
	v_add_u32_e32 v58, 0x30c0, v47
	ds_write2_b32 v58, v72, v73 offset1:1
	v_add_u32_e32 v58, 0x30c8, v47
	ds_write2_b32 v58, v74, v75 offset1:1
	v_and_b32_e32 v36, 48, v48
	v_ashrrev_i32_e32 v34, 2, v43
	v_mul_u32_u24_e32 v35, 0x104, v36
	v_and_b32_e32 v37, -4, v43
	v_add3_u32 v43, s2, v35, v37
	v_lshl_add_u32 v37, s1, 6, v34
	v_mov_b64_e32 v[34:35], s[66:67]
	s_movk_i32 s1, 0x1600
	v_mad_i64_i32 v[34:35], s[26:27], v37, s1, v[34:35]
	v_lshl_add_u64 v[34:35], v[34:35], 0, s[88:89]
	v_lshlrev_b32_e32 v184, 1, v36
	s_waitcnt lgkmcnt(0)
	s_barrier
	v_lshl_add_u64 v[44:45], v[34:35], 0, v[184:185]
	ds_read2_b32 v[34:35], v43 offset1:65
	ds_read2_b32 v[36:37], v43 offset0:130 offset1:195
	v_add_u32_e32 v46, 0x400, v43
	s_waitcnt lgkmcnt(1)
	v_cvt_pk_bf16_f32 v34, v34, v35
	s_waitcnt lgkmcnt(0)
	v_cvt_pk_bf16_f32 v35, v36, v37
	ds_read2_b32 v[36:37], v46 offset0:4 offset1:69
	s_waitcnt lgkmcnt(0)
	v_cvt_pk_bf16_f32 v36, v36, v37
	ds_read2_b32 v[46:47], v46 offset0:134 offset1:199
	s_waitcnt lgkmcnt(0)
	v_cvt_pk_bf16_f32 v37, v46, v47
	global_store_dwordx4 v[44:45], v[34:37], off
	s_nop 1
	v_add_u32_e32 v36, 0x800, v43
	v_add_u32_e32 v43, 0xc00, v43
	ds_read2_b32 v[34:35], v36 offset0:8 offset1:73
	ds_read2_b32 v[36:37], v36 offset0:138 offset1:203
	ds_read2_b32 v[46:47], v43 offset0:12 offset1:77
	ds_read2_b32 v[48:49], v43 offset0:142 offset1:207
	s_waitcnt lgkmcnt(3)
	v_cvt_pk_bf16_f32 v34, v34, v35
	s_waitcnt lgkmcnt(2)
	v_cvt_pk_bf16_f32 v35, v36, v37
	s_waitcnt lgkmcnt(1)
	v_cvt_pk_bf16_f32 v36, v46, v47
	s_waitcnt lgkmcnt(0)
	v_cvt_pk_bf16_f32 v37, v48, v49
	global_store_dwordx4 v[44:45], v[34:37], off offset:16
	s_barrier

.LBB0_508:
	s_andn2_b64 vcc, exec, s[0:1]
	s_cbranch_vccnz .LBB0_510
	s_lshl_b32 s1, s20, 2
	s_and_b32 s1, s1, 0x3fc0
	s_lshl_b32 s0, s20, 6
	s_add_i32 s88, s1, 0xffffe100
	s_nop 1
	s_and_b32 s0, s0, 0x3c0
	v_mov_b32_e32 v43, v218
	s_lshl_b64 s[26:27], s[88:89], 2
	v_readlane_b32 s68, v253, 60
	v_readlane_b32 s69, v253, 61
	s_add_u32 s26, s68, s26
	v_lshlrev_b32_e32 v46, 4, v43
	v_ashrrev_i32_e32 v36, 4, v43
	s_addc_u32 s27, s69, s27
	v_and_b32_e32 v184, 0xf0, v46
	v_lshl_add_u64 v[44:45], s[26:27], 0, v[184:185]
	v_add_u32_e32 v47, s0, v36
	s_movk_i32 s1, 0x5800
	v_mad_i64_i32 v[34:35], s[26:27], v47, s1, v[44:45]
	v_mul_lo_u32 v36, v36, s34
	v_add3_u32 v48, s2, v36, v184
	global_load_dwordx4 v[60:63], v[34:35], off nt
	s_nop 1
	v_readlane_b32 s12, v253, 8
	v_readlane_b32 s13, v253, 9
	s_nop 1
	s_mov_b32 s71, 0x42ce8ed0
	s_mov_b32 s70, 0xbfb8aa3b
	s_nop 1
	v_readlane_b32 s65, v253, 57
	s_nop 1
	v_add_u32_e32 v34, 16, v47
	v_mad_i64_i32 v[34:35], s[26:27], v34, s1, v[44:45]
	global_load_dwordx4 v[64:67], v[34:35], off nt
	v_add_u32_e32 v34, 32, v47
	v_mad_i64_i32 v[34:35], s[26:27], v34, s1, v[44:45]
	global_load_dwordx4 v[68:71], v[34:35], off nt
	v_add_u32_e32 v34, 48, v47
	v_mad_i64_i32 v[34:35], s[26:27], v34, s1, v[44:45]
	global_load_dwordx4 v[72:75], v[34:35], off nt
	s_movk_i32 s1, 0xaff
	s_waitcnt vmcnt(3)
	ds_write2_b32 v48, v60, v61 offset1:1
	ds_write2_b32 v48, v62, v63 offset0:2 offset1:3
	s_waitcnt vmcnt(2)
	v_add_u32_e32 v58, 0x1040, v48
	ds_write2_b32 v58, v64, v65 offset1:1
	v_add_u32_e32 v58, 0x1048, v48
	ds_write2_b32 v58, v66, v67 offset1:1
	s_waitcnt vmcnt(1)
	v_add_u32_e32 v58, 0x2080, v48
	ds_write2_b32 v58, v68, v69 offset1:1
	v_add_u32_e32 v58, 0x2088, v48
	ds_write2_b32 v58, v70, v71 offset1:1
	s_waitcnt vmcnt(0)
	v_add_u32_e32 v58, 0x30c0, v48
	ds_write2_b32 v58, v72, v73 offset1:1
	v_add_u32_e32 v58, 0x30c8, v48
	ds_write2_b32 v58, v74, v75 offset1:1
	v_ashrrev_i32_e32 v34, 2, v43
	v_and_b32_e32 v36, 48, v46
	v_mul_u32_u24_e32 v35, 0x104, v36
	v_and_b32_e32 v37, -4, v43
	v_add_u32_e32 v34, s88, v34
	v_add3_u32 v43, s2, v35, v37
	v_cmp_lt_i32_e32 vcc, s1, v34
	v_add_u32_e32 v35, 0xfffff500, v34
	v_mov_b32_e32 v37, 0x80
	v_cndmask_b32_e32 v34, v34, v35, vcc
	v_lshlrev_b32_e32 v35, 1, v34
	v_and_b32_e32 v35, 0xffffff00, v35
	v_cndmask_b32_e32 v37, 0, v37, vcc
	v_and_b32_e32 v34, 0x7f, v34
	v_or3_b32 v34, v34, v37, v35
	v_ashrrev_i32_e32 v35, 31, v34
	v_lshlrev_b64 v[34:35], 11, v[34:35]
	v_lshl_add_u64 v[34:35], s[12:13], 0, v[34:35]
	s_lshl_b32 s88, s0, 1
	v_lshl_add_u64 v[34:35], v[34:35], 0, s[88:89]
	v_lshlrev_b32_e32 v184, 1, v36
	s_waitcnt lgkmcnt(0)
	s_barrier
	v_lshl_add_u64 v[44:45], v[34:35], 0, v[184:185]
	ds_read2_b32 v[34:35], v43 offset1:65
	ds_read2_b32 v[36:37], v43 offset0:130 offset1:195
	v_add_u32_e32 v46, 0x400, v43
	s_waitcnt lgkmcnt(1)
	v_cvt_pk_bf16_f32 v34, v34, v35
	s_waitcnt lgkmcnt(0)
	v_cvt_pk_bf16_f32 v35, v36, v37
	ds_read2_b32 v[36:37], v46 offset0:4 offset1:69
	s_waitcnt lgkmcnt(0)
	v_cvt_pk_bf16_f32 v36, v36, v37
	ds_read2_b32 v[46:47], v46 offset0:134 offset1:199
	s_waitcnt lgkmcnt(0)
	v_cvt_pk_bf16_f32 v37, v46, v47
	global_store_dwordx4 v[44:45], v[34:37], off
	s_nop 1
	v_add_u32_e32 v36, 0x800, v43
	v_add_u32_e32 v43, 0xc00, v43
	ds_read2_b32 v[34:35], v36 offset0:8 offset1:73
	ds_read2_b32 v[36:37], v36 offset0:138 offset1:203
	ds_read2_b32 v[46:47], v43 offset0:12 offset1:77
	ds_read2_b32 v[48:49], v43 offset0:142 offset1:207
	s_waitcnt lgkmcnt(3)
	v_cvt_pk_bf16_f32 v34, v34, v35
	s_waitcnt lgkmcnt(2)
	v_cvt_pk_bf16_f32 v35, v36, v37
	s_waitcnt lgkmcnt(1)
	v_cvt_pk_bf16_f32 v36, v46, v47
	s_waitcnt lgkmcnt(0)
	v_cvt_pk_bf16_f32 v37, v48, v49
	global_store_dwordx4 v[44:45], v[34:37], off offset:16
	s_barrier

.LBB0_511:
	s_andn2_b64 vcc, exec, s[0:1]
	s_cbranch_vccnz .LBB0_513
	s_lshl_b32 s1, s20, 2
	s_and_b32 s1, s1, 0x1fc0
	s_lshl_b32 s0, s20, 6
	s_add_i32 s88, s1, 0xffffe500
	v_mov_b32_e32 v43, v218
	s_nop 1
	s_and_b32 s0, s0, 0x3c0
	s_lshl_b64 s[26:27], s[88:89], 2
	v_ashrrev_i32_e32 v36, 4, v43
	v_readlane_b32 s66, v253, 58
	v_readlane_b32 s67, v253, 59
	s_add_u32 s26, s66, s26
	v_lshlrev_b32_e32 v48, 4, v43
	v_add_u32_e32 v46, s0, v36
	s_addc_u32 s27, s67, s27
	v_and_b32_e32 v184, 0xf0, v48
	v_ashrrev_i32_e32 v47, 31, v46
	v_lshl_add_u64 v[44:45], s[26:27], 0, v[184:185]
	v_lshlrev_b64 v[34:35], 12, v[46:47]
	v_lshl_add_u64 v[34:35], v[44:45], 0, v[34:35]
	v_mul_lo_u32 v36, v36, s34
	v_add3_u32 v47, s2, v36, v184
	global_load_dwordx4 v[60:63], v[34:35], off nt
	s_nop 1
	v_readlane_b32 s10, v253, 6
	v_readlane_b32 s11, v253, 7
	s_nop 1
	s_mov_b32 s71, 0x42ce8ed0
	s_mov_b32 s70, 0xbfb8aa3b
	s_nop 1
	v_readlane_b32 s65, v253, 57
	v_readlane_b32 s68, v253, 60
	v_readlane_b32 s69, v253, 61
	s_nop 1
	v_add_u32_e32 v34, 16, v46
	v_ashrrev_i32_e32 v35, 31, v34
	v_lshlrev_b64 v[34:35], 12, v[34:35]
	v_lshl_add_u64 v[34:35], v[44:45], 0, v[34:35]
	global_load_dwordx4 v[64:67], v[34:35], off nt
	v_add_u32_e32 v34, 32, v46
	v_ashrrev_i32_e32 v35, 31, v34
	v_lshlrev_b64 v[34:35], 12, v[34:35]
	v_lshl_add_u64 v[34:35], v[44:45], 0, v[34:35]
	global_load_dwordx4 v[68:71], v[34:35], off nt
	v_add_u32_e32 v34, 48, v46
	v_ashrrev_i32_e32 v35, 31, v34
	v_lshlrev_b64 v[34:35], 12, v[34:35]
	v_lshl_add_u64 v[34:35], v[44:45], 0, v[34:35]
	global_load_dwordx4 v[72:75], v[34:35], off nt
	s_waitcnt vmcnt(3)
	ds_write2_b32 v47, v60, v61 offset1:1
	ds_write2_b32 v47, v62, v63 offset0:2 offset1:3
	s_waitcnt vmcnt(2)
	v_add_u32_e32 v58, 0x1040, v47
	ds_write2_b32 v58, v64, v65 offset1:1
	v_add_u32_e32 v58, 0x1048, v47
	ds_write2_b32 v58, v66, v67 offset1:1
	s_waitcnt vmcnt(1)
	v_add_u32_e32 v58, 0x2080, v47
	ds_write2_b32 v58, v68, v69 offset1:1
	v_add_u32_e32 v58, 0x2088, v47
	ds_write2_b32 v58, v70, v71 offset1:1
	s_waitcnt vmcnt(0)
	v_add_u32_e32 v58, 0x30c0, v47
	ds_write2_b32 v58, v72, v73 offset1:1
	v_add_u32_e32 v58, 0x30c8, v47
	ds_write2_b32 v58, v74, v75 offset1:1
	v_ashrrev_i32_e32 v34, 2, v43
	v_and_b32_e32 v36, 48, v48
	v_mul_u32_u24_e32 v35, 0x104, v36
	v_and_b32_e32 v37, -4, v43
	v_add_u32_e32 v34, s88, v34
	v_add3_u32 v43, s2, v35, v37
	v_ashrrev_i32_e32 v35, 31, v34
	v_lshlrev_b64 v[34:35], 11, v[34:35]
	v_lshl_add_u64 v[34:35], s[10:11], 0, v[34:35]
	s_lshl_b32 s88, s0, 1
	v_lshl_add_u64 v[34:35], v[34:35], 0, s[88:89]
	v_lshlrev_b32_e32 v184, 1, v36
	s_waitcnt lgkmcnt(0)
	s_barrier
	v_lshl_add_u64 v[44:45], v[34:35], 0, v[184:185]
	ds_read2_b32 v[34:35], v43 offset1:65
	ds_read2_b32 v[36:37], v43 offset0:130 offset1:195
	v_add_u32_e32 v46, 0x400, v43
	s_waitcnt lgkmcnt(1)
	v_cvt_pk_bf16_f32 v34, v34, v35
	s_waitcnt lgkmcnt(0)
	v_cvt_pk_bf16_f32 v35, v36, v37
	ds_read2_b32 v[36:37], v46 offset0:4 offset1:69
	s_waitcnt lgkmcnt(0)
	v_cvt_pk_bf16_f32 v36, v36, v37
	ds_read2_b32 v[46:47], v46 offset0:134 offset1:199
	s_waitcnt lgkmcnt(0)
	v_cvt_pk_bf16_f32 v37, v46, v47
	global_store_dwordx4 v[44:45], v[34:37], off
	s_nop 1
	v_add_u32_e32 v36, 0x800, v43
	v_add_u32_e32 v43, 0xc00, v43
	ds_read2_b32 v[34:35], v36 offset0:8 offset1:73
	ds_read2_b32 v[36:37], v36 offset0:138 offset1:203
	ds_read2_b32 v[46:47], v43 offset0:12 offset1:77
	ds_read2_b32 v[48:49], v43 offset0:142 offset1:207
	s_waitcnt lgkmcnt(3)
	v_cvt_pk_bf16_f32 v34, v34, v35
	s_waitcnt lgkmcnt(2)
	v_cvt_pk_bf16_f32 v35, v36, v37
	s_waitcnt lgkmcnt(1)
	v_cvt_pk_bf16_f32 v36, v46, v47
	s_waitcnt lgkmcnt(0)
	v_cvt_pk_bf16_f32 v37, v48, v49
	global_store_dwordx4 v[44:45], v[34:37], off offset:16
	s_barrier

.LBB0_514:
	s_andn2_b64 vcc, exec, s[0:1]
	s_cbranch_vccnz .LBB0_516
	s_add_i32 s0, s20, 0xfffffa00
	s_lshr_b32 s88, s0, 6
	s_nop 1
	s_lshl_b64 s[0:1], s[88:89], 20
	v_readlane_b32 s64, v253, 56
	v_readlane_b32 s65, v253, 57
	s_add_u32 s27, s64, s0
	s_nop 1
	s_addc_u32 s29, s65, s1
	s_lshl_b32 s0, s20, 6
	s_and_b32 s23, s0, 0xc0
	s_lshl_b32 s0, s20, 4
	s_nop 1
	s_and_b32 s26, s0, 0x3c0
	s_lshl_b64 s[0:1], s[88:89], 19
	v_readlane_b32 s60, v253, 4
	v_readlane_b32 s61, v253, 5
	s_add_u32 s0, s60, s0
	v_mov_b32_e32 v43, v218
	s_addc_u32 s1, s61, s1
	s_lshl_b32 s28, s26, 2
	v_ashrrev_i32_e32 v36, 4, v43
	s_add_u32 s28, s27, s28
	v_lshlrev_b32_e32 v48, 4, v43
	v_add_u32_e32 v46, s23, v36
	s_addc_u32 s29, s29, 0
	v_and_b32_e32 v184, 0xf0, v48
	v_ashrrev_i32_e32 v47, 31, v46
	v_lshl_add_u64 v[44:45], s[28:29], 0, v[184:185]
	v_lshlrev_b64 v[34:35], 12, v[46:47]
	v_lshl_add_u64 v[34:35], v[44:45], 0, v[34:35]
	v_mul_lo_u32 v36, v36, s34
	v_add3_u32 v47, s2, v36, v184
	global_load_dwordx4 v[60:63], v[34:35], off nt
	s_lshl_b32 s88, s23, 1
	s_nop 1
	s_mov_b32 s71, 0x42ce8ed0
	s_mov_b32 s70, 0xbfb8aa3b
	s_nop 1
	v_readlane_b32 s65, v253, 9
	s_nop 1
	v_readlane_b32 s68, v253, 12
	v_readlane_b32 s69, v253, 13
	v_add_u32_e32 v34, 16, v46
	v_ashrrev_i32_e32 v35, 31, v34
	v_lshlrev_b64 v[34:35], 12, v[34:35]
	v_lshl_add_u64 v[34:35], v[44:45], 0, v[34:35]
	global_load_dwordx4 v[64:67], v[34:35], off nt
	v_add_u32_e32 v34, 32, v46
	v_ashrrev_i32_e32 v35, 31, v34
	v_lshlrev_b64 v[34:35], 12, v[34:35]
	v_lshl_add_u64 v[34:35], v[44:45], 0, v[34:35]
	global_load_dwordx4 v[68:71], v[34:35], off nt
	v_add_u32_e32 v34, 48, v46
	v_ashrrev_i32_e32 v35, 31, v34
	v_lshlrev_b64 v[34:35], 12, v[34:35]
	v_lshl_add_u64 v[34:35], v[44:45], 0, v[34:35]
	global_load_dwordx4 v[72:75], v[34:35], off nt
	s_waitcnt vmcnt(3)
	ds_write2_b32 v47, v60, v61 offset1:1
	ds_write2_b32 v47, v62, v63 offset0:2 offset1:3
	s_waitcnt vmcnt(2)
	v_add_u32_e32 v58, 0x1040, v47
	ds_write2_b32 v58, v64, v65 offset1:1
	v_add_u32_e32 v58, 0x1048, v47
	ds_write2_b32 v58, v66, v67 offset1:1
	s_waitcnt vmcnt(1)
	v_add_u32_e32 v58, 0x2080, v47
	ds_write2_b32 v58, v68, v69 offset1:1
	v_add_u32_e32 v58, 0x2088, v47
	ds_write2_b32 v58, v70, v71 offset1:1
	s_waitcnt vmcnt(0)
	v_add_u32_e32 v58, 0x30c0, v47
	ds_write2_b32 v58, v72, v73 offset1:1
	v_add_u32_e32 v58, 0x30c8, v47
	ds_write2_b32 v58, v74, v75 offset1:1
	v_ashrrev_i32_e32 v34, 2, v43
	v_and_b32_e32 v36, 48, v48
	v_mul_u32_u24_e32 v35, 0x104, v36
	v_and_b32_e32 v37, -4, v43
	v_add_u32_e32 v34, s26, v34
	v_add3_u32 v43, s2, v35, v37
	v_ashrrev_i32_e32 v35, 31, v34
	v_lshlrev_b64 v[34:35], 9, v[34:35]
	v_lshl_add_u64 v[34:35], s[0:1], 0, v[34:35]
	v_lshl_add_u64 v[34:35], v[34:35], 0, s[88:89]
	v_lshlrev_b32_e32 v184, 1, v36
	s_waitcnt lgkmcnt(0)
	s_barrier
	v_lshl_add_u64 v[44:45], v[34:35], 0, v[184:185]
	ds_read2_b32 v[34:35], v43 offset1:65
	ds_read2_b32 v[36:37], v43 offset0:130 offset1:195
	v_add_u32_e32 v46, 0x400, v43
	s_waitcnt lgkmcnt(1)
	v_cvt_pk_bf16_f32 v34, v34, v35
	s_waitcnt lgkmcnt(0)
	v_cvt_pk_bf16_f32 v35, v36, v37
	ds_read2_b32 v[36:37], v46 offset0:4 offset1:69
	s_waitcnt lgkmcnt(0)
	v_cvt_pk_bf16_f32 v36, v36, v37
	ds_read2_b32 v[46:47], v46 offset0:134 offset1:199
	s_waitcnt lgkmcnt(0)
	v_cvt_pk_bf16_f32 v37, v46, v47
	global_store_dwordx4 v[44:45], v[34:37], off
	s_nop 1
	v_add_u32_e32 v36, 0x800, v43
	v_add_u32_e32 v43, 0xc00, v43
	ds_read2_b32 v[34:35], v36 offset0:8 offset1:73
	ds_read2_b32 v[36:37], v36 offset0:138 offset1:203
	ds_read2_b32 v[46:47], v43 offset0:12 offset1:77
	ds_read2_b32 v[48:49], v43 offset0:142 offset1:207
	s_waitcnt lgkmcnt(3)
	v_cvt_pk_bf16_f32 v34, v34, v35
	s_waitcnt lgkmcnt(2)
	v_cvt_pk_bf16_f32 v35, v36, v37
	s_waitcnt lgkmcnt(1)
	v_cvt_pk_bf16_f32 v36, v46, v47
	s_waitcnt lgkmcnt(0)
	v_cvt_pk_bf16_f32 v37, v48, v49
	global_store_dwordx4 v[44:45], v[34:37], off offset:16
	s_barrier

.LBB0_517:
	s_lshl_b32 s0, s20, 2
	s_and_b32 s23, s0, 0xffffffc0
	s_add_i32 s0, s23, 0x100
	s_cmpk_lt_i32 s23, 0x700
	s_cselect_b32 s0, s23, s0
	s_lshl_b32 s1, s20, 6
	s_and_b32 s26, s1, 0x3c0
	s_ashr_i32 s1, s0, 31
	s_nop 1
	v_mov_b32_e32 v43, v218
	s_lshl_b64 s[0:1], s[0:1], 2
	v_readlane_b32 s18, v253, 46
	v_readlane_b32 s19, v253, 47
	s_add_u32 s0, s18, s0
	v_lshlrev_b32_e32 v46, 4, v43
	v_ashrrev_i32_e32 v36, 4, v43
	s_addc_u32 s1, s19, s1
	v_and_b32_e32 v184, 0xf0, v46
	v_lshl_add_u64 v[44:45], s[0:1], 0, v[184:185]
	v_add_u32_e32 v47, s26, v36
	v_mad_i64_i32 v[34:35], s[0:1], v47, s35, v[44:45]
	v_mul_lo_u32 v36, v36, s34
	v_add3_u32 v48, s2, v36, v184
	global_load_dwordx4 v[60:63], v[34:35], off nt
	s_nop 1
	v_readlane_b32 s6, v253, 2
	v_readlane_b32 s7, v253, 3
	s_lshl_b32 s88, s26, 1
	s_nop 1
	v_add_u32_e32 v34, 16, v47
	v_mad_i64_i32 v[34:35], s[0:1], v34, s35, v[44:45]
	global_load_dwordx4 v[64:67], v[34:35], off nt
	v_add_u32_e32 v34, 32, v47
	v_mad_i64_i32 v[34:35], s[0:1], v34, s35, v[44:45]
	global_load_dwordx4 v[68:71], v[34:35], off nt
	v_add_u32_e32 v34, 48, v47
	v_mad_i64_i32 v[34:35], s[0:1], v34, s35, v[44:45]
	global_load_dwordx4 v[72:75], v[34:35], off nt
	s_waitcnt vmcnt(3)
	ds_write2_b32 v48, v60, v61 offset1:1
	ds_write2_b32 v48, v62, v63 offset0:2 offset1:3
	s_waitcnt vmcnt(2)
	v_add_u32_e32 v58, 0x1040, v48
	ds_write2_b32 v58, v64, v65 offset1:1
	v_add_u32_e32 v58, 0x1048, v48
	ds_write2_b32 v58, v66, v67 offset1:1
	s_waitcnt vmcnt(1)
	v_add_u32_e32 v58, 0x2080, v48
	ds_write2_b32 v58, v68, v69 offset1:1
	v_add_u32_e32 v58, 0x2088, v48
	ds_write2_b32 v58, v70, v71 offset1:1
	s_waitcnt vmcnt(0)
	v_add_u32_e32 v58, 0x30c0, v48
	ds_write2_b32 v58, v72, v73 offset1:1
	v_add_u32_e32 v58, 0x30c8, v48
	ds_write2_b32 v58, v74, v75 offset1:1
	v_ashrrev_i32_e32 v34, 2, v43
	v_and_b32_e32 v36, 48, v46
	v_mul_u32_u24_e32 v35, 0x104, v36
	v_and_b32_e32 v37, -4, v43
	v_add_u32_e32 v34, s23, v34
	v_add3_u32 v43, s2, v35, v37
	v_ashrrev_i32_e32 v35, 31, v34
	v_lshlrev_b64 v[34:35], 11, v[34:35]
	v_lshl_add_u64 v[34:35], s[6:7], 0, v[34:35]
	v_lshl_add_u64 v[34:35], v[34:35], 0, s[88:89]
	v_lshlrev_b32_e32 v184, 1, v36
	s_waitcnt lgkmcnt(0)
	s_barrier
	v_lshl_add_u64 v[44:45], v[34:35], 0, v[184:185]
	ds_read2_b32 v[34:35], v43 offset1:65
	ds_read2_b32 v[36:37], v43 offset0:130 offset1:195
	v_add_u32_e32 v46, 0x400, v43
	s_waitcnt lgkmcnt(1)
	v_cvt_pk_bf16_f32 v34, v34, v35
	s_waitcnt lgkmcnt(0)
	v_cvt_pk_bf16_f32 v35, v36, v37
	ds_read2_b32 v[36:37], v46 offset0:4 offset1:69
	s_waitcnt lgkmcnt(0)
	v_cvt_pk_bf16_f32 v36, v36, v37
	ds_read2_b32 v[46:47], v46 offset0:134 offset1:199
	s_waitcnt lgkmcnt(0)
	v_cvt_pk_bf16_f32 v37, v46, v47
	global_store_dwordx4 v[44:45], v[34:37], off
	s_nop 1
	v_add_u32_e32 v36, 0x800, v43
	v_add_u32_e32 v43, 0xc00, v43
	ds_read2_b32 v[34:35], v36 offset0:8 offset1:73
	ds_read2_b32 v[36:37], v36 offset0:138 offset1:203
	ds_read2_b32 v[46:47], v43 offset0:12 offset1:77
	ds_read2_b32 v[48:49], v43 offset0:142 offset1:207
	s_waitcnt lgkmcnt(3)
	v_cvt_pk_bf16_f32 v34, v34, v35
	s_waitcnt lgkmcnt(2)
	v_cvt_pk_bf16_f32 v35, v36, v37
	s_waitcnt lgkmcnt(1)
	v_cvt_pk_bf16_f32 v36, v46, v47
	s_waitcnt lgkmcnt(0)
	v_cvt_pk_bf16_f32 v37, v48, v49
	global_store_dwordx4 v[44:45], v[34:37], off offset:16
	s_barrier
	s_branch .LBB0_484

.LBB0_521:
	s_or_b64 exec, exec, s[28:29]
	s_nop 1
	v_readlane_b32 s16, v253, 12
	v_readlane_b32 s17, v253, 13
	v_cvt_pk_bf16_f32 v2, v2, v5
	v_cvt_pk_bf16_f32 v3, v6, v7
	v_cvt_pk_bf16_f32 v4, v8, v9
	v_cvt_pk_bf16_f32 v5, v10, v13
	s_nop 1
	s_nop 0
	v_lshl_add_u64 v[0:1], v[0:1], 1, s[16:17]
	s_nop 1
	global_store_dwordx4 v[0:1], v[2:5], off

.LBB0_525:
	s_cmpk_gt_u32 s22, 0x103f
	s_cbranch_scc0 .LBB0_553
	s_cmpk_gt_u32 s22, 0x113f
	s_cbranch_scc0 .LBB0_543
	s_and_saveexec_b64 s[28:29], s[36:37]
	s_nop 1
	s_cbranch_execz .LBB0_537
	v_mov_b32_e32 v184, v40
	v_mov_b32_e32 v2, v81
	v_mov_b64_e32 v[0:1], v[40:41]
	s_and_saveexec_b64 s[30:31], s[44:45]
	s_cbranch_execz .LBB0_534
	s_nop 1
	s_mov_b64 s[34:35], 0
	v_mov_b32_e32 v2, v49
	v_mov_b32_e32 v3, v83
	v_mov_b64_e32 v[0:1], v[54:55]
	v_readlane_b32 s6, v253, 34
	v_readlane_b32 s7, v253, 35
	v_readlane_b32 s10, v253, 38
	v_readlane_b32 s11, v253, 39
	s_nop 1

.LBB0_534:
	s_or_b64 exec, exec, s[30:31]
	s_nop 1
	s_and_b64 s[0:1], exec, s[0:1]
	v_readlane_b32 s6, v253, 34
	v_readlane_b32 s7, v253, 35
	v_readlane_b32 s10, v253, 38
	v_readlane_b32 s11, v253, 39
	s_nop 1
	s_mov_b64 exec, s[0:1]
	s_cbranch_execz .LBB0_537
	v_add_u32_e32 v2, s2, v2
	v_lshl_add_u64 v[0:1], v[0:1], 2, s[6:7]
	s_mov_b64 s[0:1], 0

.LBB0_538:
	s_mov_b32 s26, 0xfffa6000
	v_add_co_u32_e32 v2, vcc, s26, v58
	s_mov_b32 s26, 0xfffac000
	s_nop 0
	v_addc_co_u32_e32 v3, vcc, -1, v59, vcc
	global_load_dword v78, v[2:3], off
	v_add_co_u32_e32 v2, vcc, s26, v58
	s_mov_b32 s26, 0xfffb2000
	s_nop 0
	v_addc_co_u32_e32 v3, vcc, -1, v59, vcc
	global_load_dword v80, v[2:3], off
	v_add_co_u32_e32 v2, vcc, s26, v58
	s_mov_b32 s26, 0xfffb8000
	s_nop 0
	v_addc_co_u32_e32 v3, vcc, -1, v59, vcc
	global_load_dword v82, v[2:3], off
	v_add_co_u32_e32 v2, vcc, s26, v58
	s_mov_b32 s26, 0xfffbe000
	s_nop 0
	v_addc_co_u32_e32 v3, vcc, -1, v59, vcc
	global_load_dword v86, v[2:3], off
	v_add_co_u32_e32 v2, vcc, s26, v58
	s_mov_b32 s26, 0xfffc4000
	s_nop 0
	v_addc_co_u32_e32 v3, vcc, -1, v59, vcc
	global_load_dword v88, v[2:3], off
	v_add_co_u32_e32 v2, vcc, s26, v58
	s_mov_b32 s26, 0xfffca000
	s_nop 0
	v_addc_co_u32_e32 v3, vcc, -1, v59, vcc
	global_load_dword v72, v[2:3], off
	v_add_co_u32_e32 v2, vcc, s26, v58
	s_mov_b32 s26, 0xfffd0000
	s_nop 0
	v_addc_co_u32_e32 v3, vcc, -1, v59, vcc
	global_load_dword v73, v[2:3], off
	v_add_co_u32_e32 v2, vcc, s26, v58
	s_mov_b32 s26, 0xfffd6000
	s_nop 0
	v_addc_co_u32_e32 v3, vcc, -1, v59, vcc
	global_load_dword v74, v[2:3], off
	v_add_co_u32_e32 v2, vcc, s26, v58
	s_mov_b32 s26, 0xfffdc000
	s_nop 0
	v_addc_co_u32_e32 v3, vcc, -1, v59, vcc
	global_load_dword v75, v[2:3], off
	v_add_co_u32_e32 v2, vcc, s26, v58
	s_mov_b32 s26, 0xfffe2000
	s_nop 0
	v_addc_co_u32_e32 v3, vcc, -1, v59, vcc
	global_load_dword v68, v[2:3], off
	v_add_co_u32_e32 v2, vcc, s26, v58
	s_mov_b32 s26, 0xfffe8000
	s_nop 0
	v_addc_co_u32_e32 v3, vcc, -1, v59, vcc
	global_load_dword v69, v[2:3], off
	v_add_co_u32_e32 v2, vcc, s26, v58
	s_mov_b32 s26, 0xfffee000
	s_nop 0
	v_addc_co_u32_e32 v3, vcc, -1, v59, vcc
	global_load_dword v70, v[2:3], off
	v_add_co_u32_e32 v2, vcc, s26, v58
	s_mov_b32 s26, 0xffff4000
	s_nop 0
	v_addc_co_u32_e32 v3, vcc, -1, v59, vcc
	global_load_dword v71, v[2:3], off
	v_add_co_u32_e32 v2, vcc, s26, v58
	s_movk_i32 s26, 0xa000
	s_nop 0
	v_addc_co_u32_e32 v3, vcc, -1, v59, vcc
	global_load_dword v66, v[2:3], off
	v_add_co_u32_e32 v2, vcc, s26, v58
	v_add_u32_e32 v87, 0x800c, v53
	s_nop 0
	v_addc_co_u32_e32 v3, vcc, -1, v59, vcc
	global_load_dword v67, v[2:3], off
	global_load_dword v64, v[58:59], off
	ds_read_b96 v[2:4], v53 offset:32768
	v_add_u32_e32 v92, 16, v92
	v_cmp_ge_i32_e32 vcc, v92, v79
	v_lshl_add_u64 v[58:59], v[58:59], 0, s[82:83]
	s_or_b64 s[0:1], vcc, s[0:1]
	s_waitcnt vmcnt(15) lgkmcnt(0)
	v_fmac_f32_e32 v93, v78, v2
	s_waitcnt vmcnt(14)
	v_fmac_f32_e32 v93, v80, v3
	s_waitcnt vmcnt(13)
	v_fmac_f32_e32 v93, v82, v4
	ds_read_b128 v[2:5], v53
	ds_read_b128 v[32:35], v53 offset:16
	ds_read_b128 v[20:23], v53 offset:32
	ds_read_b128 v[16:19], v53 offset:48
	ds_read_b128 v[36:39], v53 offset:4112
	ds_read_b128 v[10:13], v53 offset:4096
	s_waitcnt lgkmcnt(5)
	v_mov_b32_e32 v6, v2
	v_mov_b32_e32 v2, v4
	s_waitcnt lgkmcnt(0)
	v_mov_b32_e32 v7, v10
	v_pk_fma_f32 v[0:1], v[78:79], v[6:7], v[0:1] op_sel_hi:[0,1,1]
	v_mov_b32_e32 v10, v3
	v_pk_fma_f32 v[0:1], v[80:81], v[10:11], v[0:1] op_sel_hi:[0,1,1]
	v_mov_b32_e32 v3, v12
	v_pk_fma_f32 v[0:1], v[82:83], v[2:3], v[0:1] op_sel_hi:[0,1,1]
	v_mov_b32_e32 v12, v5
	s_waitcnt vmcnt(12)
	v_pk_fma_f32 v[0:1], v[86:87], v[12:13], v[0:1] op_sel_hi:[0,1,1]
	v_mov_b32_e32 v2, v32
	v_mov_b32_e32 v3, v36
	s_waitcnt vmcnt(11)
	v_pk_fma_f32 v[84:85], v[88:89], v[2:3], v[0:1] op_sel_hi:[0,1,1]
	ds_read_b128 v[24:27], v53 offset:8208
	ds_read_b128 v[28:31], v53 offset:12304
	ds_read_b128 v[0:3], v53 offset:8192
	ds_read_b128 v[4:7], v53 offset:12288
	v_mov_b32_e32 v36, v33
	s_waitcnt lgkmcnt(1)
	v_mov_b32_e32 v10, v0
	s_waitcnt lgkmcnt(0)
	v_mov_b32_e32 v11, v4
	v_pk_fma_f32 v[8:9], v[78:79], v[10:11], v[8:9] op_sel_hi:[0,1,1]
	v_mov_b32_e32 v4, v1
	v_pk_fma_f32 v[0:1], v[80:81], v[4:5], v[8:9] op_sel_hi:[0,1,1]
	v_mov_b32_e32 v4, v2
	v_mov_b32_e32 v5, v6
	v_pk_fma_f32 v[0:1], v[82:83], v[4:5], v[0:1] op_sel_hi:[0,1,1]
	v_mov_b32_e32 v6, v3
	v_pk_fma_f32 v[0:1], v[86:87], v[6:7], v[0:1] op_sel_hi:[0,1,1]
	v_mov_b32_e32 v2, v24
	v_mov_b32_e32 v3, v28
	v_pk_fma_f32 v[76:77], v[88:89], v[2:3], v[0:1] op_sel_hi:[0,1,1]
	ds_read_b128 v[8:11], v53 offset:16400
	ds_read_b128 v[12:15], v53 offset:20496
	ds_read_b128 v[0:3], v53 offset:16384
	ds_read_b128 v[4:7], v53 offset:20480
	s_waitcnt vmcnt(9)
	v_mov_b32_e32 v32, v73
	s_waitcnt vmcnt(7)
	v_mov_b32_e32 v24, v75
	v_mov_b32_e32 v28, v25
	s_waitcnt lgkmcnt(1)
	v_mov_b32_e32 v94, v0
	s_waitcnt lgkmcnt(0)
	v_mov_b32_e32 v95, v4
	v_pk_fma_f32 v[60:61], v[78:79], v[94:95], v[60:61] op_sel_hi:[0,1,1]
	v_mov_b32_e32 v4, v1
	v_pk_fma_f32 v[0:1], v[80:81], v[4:5], v[60:61] op_sel_hi:[0,1,1]
	v_mov_b32_e32 v4, v2
	v_mov_b32_e32 v5, v6
	v_pk_fma_f32 v[0:1], v[82:83], v[4:5], v[0:1] op_sel_hi:[0,1,1]
	v_mov_b32_e32 v6, v3
	v_pk_fma_f32 v[0:1], v[86:87], v[6:7], v[0:1] op_sel_hi:[0,1,1]
	v_mov_b32_e32 v2, v8
	v_mov_b32_e32 v3, v12
	v_pk_fma_f32 v[60:61], v[88:89], v[2:3], v[0:1] op_sel_hi:[0,1,1]
	ds_read_b128 v[0:3], v53 offset:24592
	ds_read_b128 v[4:7], v53 offset:28688
	ds_read_b128 v[94:97], v53 offset:24576
	ds_read_b128 v[98:101], v53 offset:28672
	v_mov_b32_e32 v12, v9
	v_mov_b32_e32 v9, v38
	v_mov_b32_e32 v38, v35
	s_waitcnt lgkmcnt(1)
	v_mov_b32_e32 v102, v94
	s_waitcnt lgkmcnt(0)
	v_mov_b32_e32 v103, v98
	v_pk_fma_f32 v[62:63], v[78:79], v[102:103], v[62:63] op_sel_hi:[0,1,1]
	v_mov_b32_e32 v98, v95
	v_pk_fma_f32 v[62:63], v[80:81], v[98:99], v[62:63] op_sel_hi:[0,1,1]
	v_mov_b32_e32 v94, v96
	v_mov_b32_e32 v95, v100
	v_pk_fma_f32 v[62:63], v[82:83], v[94:95], v[62:63] op_sel_hi:[0,1,1]
	v_mov_b32_e32 v100, v97
	v_pk_fma_f32 v[62:63], v[86:87], v[100:101], v[62:63] op_sel_hi:[0,1,1]
	v_mov_b32_e32 v94, v0
	v_mov_b32_e32 v95, v4
	v_pk_fma_f32 v[62:63], v[88:89], v[94:95], v[62:63] op_sel_hi:[0,1,1]
	ds_read2_b32 v[94:95], v87 offset1:1
	v_mov_b32_e32 v87, v88
	v_mov_b32_e32 v4, v1
	v_pk_fma_f32 v[12:13], v[72:73], v[12:13], v[60:61] op_sel_hi:[0,1,1]
	v_pk_fma_f32 v[4:5], v[72:73], v[4:5], v[62:63] op_sel_hi:[0,1,1]
	s_waitcnt lgkmcnt(0)
	v_pk_mul_f32 v[86:87], v[86:87], v[94:95]
	s_nop 0
	v_add_f32_e32 v0, v93, v86
	v_add_f32_e32 v8, v0, v87
	v_add_u32_e32 v0, 0x8014, v53
	ds_read2_b32 v[0:1], v0 offset1:1
	s_waitcnt lgkmcnt(0)
	v_pk_mul_f32 v[0:1], v[72:73], v[0:1]
	s_nop 0
	v_add_f32_e32 v0, v8, v0
	v_add_f32_e32 v8, v0, v1
	v_add_u32_e32 v0, 0x801c, v53
	ds_read2_b32 v[0:1], v0 offset1:1
	s_waitcnt lgkmcnt(0)
	v_pk_mul_f32 v[0:1], v[74:75], v[0:1]
	s_nop 0
	v_add_f32_e32 v0, v8, v0
	v_add_f32_e32 v8, v0, v1
	v_add_u32_e32 v0, 0x8024, v53
	ds_read2_b32 v[0:1], v0 offset1:1
	s_waitcnt vmcnt(5) lgkmcnt(0)
	v_pk_mul_f32 v[0:1], v[68:69], v[0:1]
	s_nop 0
	v_add_f32_e32 v0, v8, v0
	v_add_f32_e32 v8, v0, v1
	v_add_u32_e32 v0, 0x802c, v53
	ds_read2_b32 v[0:1], v0 offset1:1
	s_waitcnt vmcnt(3) lgkmcnt(0)
	v_pk_mul_f32 v[0:1], v[70:71], v[0:1]
	s_nop 0
	v_add_f32_e32 v0, v8, v0
	v_add_f32_e32 v8, v0, v1
	v_add_u32_e32 v0, 0x8034, v53
	ds_read2_b32 v[0:1], v0 offset1:1
	s_waitcnt vmcnt(1) lgkmcnt(0)
	v_pk_mul_f32 v[0:1], v[66:67], v[0:1]
	s_nop 0
	v_add_f32_e32 v0, v8, v0
	v_add_f32_e32 v93, v0, v1
	v_pk_fma_f32 v[0:1], v[72:73], v[36:37], v[84:85] op_sel_hi:[0,1,1]
	v_mov_b32_e32 v8, v34
	ds_read_b128 v[34:37], v53 offset:4128
	v_pk_fma_f32 v[0:1], v[32:33], v[8:9], v[0:1] op_sel_hi:[0,1,1]
	v_pk_fma_f32 v[0:1], v[74:75], v[38:39], v[0:1] op_sel_hi:[0,1,1]
	v_mov_b32_e32 v8, v20
	v_mov_b32_e32 v20, v69
	s_waitcnt lgkmcnt(0)
	v_mov_b32_e32 v9, v34
	v_pk_fma_f32 v[0:1], v[24:25], v[8:9], v[0:1] op_sel_hi:[0,1,1]
	v_mov_b32_e32 v34, v21
	v_pk_fma_f32 v[0:1], v[68:69], v[34:35], v[0:1] op_sel_hi:[0,1,1]
	v_mov_b32_e32 v8, v22
	v_mov_b32_e32 v9, v36
	v_pk_fma_f32 v[0:1], v[20:21], v[8:9], v[0:1] op_sel_hi:[0,1,1]
	v_mov_b32_e32 v36, v23
	v_pk_fma_f32 v[0:1], v[70:71], v[36:37], v[0:1] op_sel_hi:[0,1,1]
	ds_read_b128 v[34:37], v53 offset:4144
	v_mov_b32_e32 v22, v71
	v_mov_b32_e32 v8, v16
	v_mov_b32_e32 v16, v67
	s_waitcnt lgkmcnt(0)
	v_mov_b32_e32 v9, v34
	v_pk_fma_f32 v[0:1], v[22:23], v[8:9], v[0:1] op_sel_hi:[0,1,1]
	v_mov_b32_e32 v34, v17
	v_pk_fma_f32 v[0:1], v[66:67], v[34:35], v[0:1] op_sel_hi:[0,1,1]
	v_mov_b32_e32 v8, v18
	v_mov_b32_e32 v9, v36
	v_pk_fma_f32 v[0:1], v[16:17], v[8:9], v[0:1] op_sel_hi:[0,1,1]
	v_mov_b32_e32 v36, v19
	s_waitcnt vmcnt(0)
	v_pk_fma_f32 v[0:1], v[64:65], v[36:37], v[0:1] op_sel_hi:[0,1,1]
	v_pk_fma_f32 v[8:9], v[72:73], v[28:29], v[76:77] op_sel_hi:[0,1,1]
	v_mov_b32_e32 v18, v26
	v_mov_b32_e32 v19, v30
	v_mov_b32_e32 v30, v27
	ds_read_b128 v[26:29], v53 offset:8224
	ds_read_b128 v[34:37], v53 offset:12320
	v_pk_fma_f32 v[8:9], v[32:33], v[18:19], v[8:9] op_sel_hi:[0,1,1]
	v_pk_fma_f32 v[8:9], v[74:75], v[30:31], v[8:9] op_sel_hi:[0,1,1]
	s_waitcnt lgkmcnt(1)
	v_mov_b32_e32 v18, v26
	s_waitcnt lgkmcnt(0)
	v_mov_b32_e32 v19, v34
	v_pk_fma_f32 v[8:9], v[24:25], v[18:19], v[8:9] op_sel_hi:[0,1,1]
	v_mov_b32_e32 v34, v27
	v_pk_fma_f32 v[8:9], v[68:69], v[34:35], v[8:9] op_sel_hi:[0,1,1]
	v_mov_b32_e32 v18, v28
	v_mov_b32_e32 v19, v36
	v_pk_fma_f32 v[8:9], v[20:21], v[18:19], v[8:9] op_sel_hi:[0,1,1]
	v_mov_b32_e32 v36, v29
	v_pk_fma_f32 v[8:9], v[70:71], v[36:37], v[8:9] op_sel_hi:[0,1,1]
	ds_read_b128 v[26:29], v53 offset:8240
	ds_read_b128 v[34:37], v53 offset:12336
	s_waitcnt lgkmcnt(1)
	v_mov_b32_e32 v18, v26
	s_waitcnt lgkmcnt(0)
	v_mov_b32_e32 v19, v34
	v_pk_fma_f32 v[8:9], v[22:23], v[18:19], v[8:9] op_sel_hi:[0,1,1]
	v_mov_b32_e32 v34, v27
	v_pk_fma_f32 v[8:9], v[66:67], v[34:35], v[8:9] op_sel_hi:[0,1,1]
	v_mov_b32_e32 v18, v28
	v_mov_b32_e32 v19, v36
	v_pk_fma_f32 v[8:9], v[16:17], v[18:19], v[8:9] op_sel_hi:[0,1,1]
	v_mov_b32_e32 v18, v10
	v_mov_b32_e32 v19, v14
	v_pk_fma_f32 v[12:13], v[32:33], v[18:19], v[12:13] op_sel_hi:[0,1,1]
	v_mov_b32_e32 v14, v11
	v_mov_b32_e32 v36, v29
	v_pk_fma_f32 v[14:15], v[74:75], v[14:15], v[12:13] op_sel_hi:[0,1,1]
	ds_read_b128 v[10:13], v53 offset:16416
	ds_read_b128 v[26:29], v53 offset:20512
	v_pk_fma_f32 v[8:9], v[64:65], v[36:37], v[8:9] op_sel_hi:[0,1,1]
	s_waitcnt lgkmcnt(1)
	v_mov_b32_e32 v18, v10
	s_waitcnt lgkmcnt(0)
	v_mov_b32_e32 v19, v26
	v_pk_fma_f32 v[14:15], v[24:25], v[18:19], v[14:15] op_sel_hi:[0,1,1]
	v_mov_b32_e32 v26, v11
	v_pk_fma_f32 v[10:11], v[68:69], v[26:27], v[14:15] op_sel_hi:[0,1,1]
	v_mov_b32_e32 v14, v12
	v_mov_b32_e32 v15, v28
	v_pk_fma_f32 v[10:11], v[20:21], v[14:15], v[10:11] op_sel_hi:[0,1,1]
	v_mov_b32_e32 v28, v13
	v_pk_fma_f32 v[14:15], v[70:71], v[28:29], v[10:11] op_sel_hi:[0,1,1]
	ds_read_b128 v[10:13], v53 offset:16432
	ds_read_b128 v[26:29], v53 offset:20528
	s_waitcnt lgkmcnt(1)
	v_mov_b32_e32 v18, v10
	s_waitcnt lgkmcnt(0)
	v_mov_b32_e32 v19, v26
	v_pk_fma_f32 v[14:15], v[22:23], v[18:19], v[14:15] op_sel_hi:[0,1,1]
	v_mov_b32_e32 v26, v11
	v_pk_fma_f32 v[10:11], v[66:67], v[26:27], v[14:15] op_sel_hi:[0,1,1]
	v_mov_b32_e32 v14, v12
	v_mov_b32_e32 v15, v28
	v_pk_fma_f32 v[10:11], v[16:17], v[14:15], v[10:11] op_sel_hi:[0,1,1]
	v_mov_b32_e32 v28, v13
	v_pk_fma_f32 v[60:61], v[64:65], v[28:29], v[10:11] op_sel_hi:[0,1,1]
	v_mov_b32_e32 v10, v2
	v_mov_b32_e32 v11, v6
	v_pk_fma_f32 v[4:5], v[32:33], v[10:11], v[4:5] op_sel_hi:[0,1,1]
	v_mov_b32_e32 v6, v3
	v_pk_fma_f32 v[6:7], v[74:75], v[6:7], v[4:5] op_sel_hi:[0,1,1]
	ds_read_b128 v[2:5], v53 offset:24608
	ds_read_b128 v[10:13], v53 offset:28704
	s_waitcnt lgkmcnt(1)
	v_mov_b32_e32 v14, v2
	s_waitcnt lgkmcnt(0)
	v_mov_b32_e32 v15, v10
	v_pk_fma_f32 v[6:7], v[24:25], v[14:15], v[6:7] op_sel_hi:[0,1,1]
	v_mov_b32_e32 v10, v3
	v_pk_fma_f32 v[2:3], v[68:69], v[10:11], v[6:7] op_sel_hi:[0,1,1]
	v_mov_b32_e32 v6, v4
	v_mov_b32_e32 v7, v12
	v_pk_fma_f32 v[2:3], v[20:21], v[6:7], v[2:3] op_sel_hi:[0,1,1]
	v_mov_b32_e32 v12, v5
	v_pk_fma_f32 v[6:7], v[70:71], v[12:13], v[2:3] op_sel_hi:[0,1,1]
	ds_read_b128 v[2:5], v53 offset:24624
	ds_read_b128 v[10:13], v53 offset:28720
	s_waitcnt lgkmcnt(1)
	v_mov_b32_e32 v14, v2
	s_waitcnt lgkmcnt(0)
	v_mov_b32_e32 v15, v10
	v_pk_fma_f32 v[6:7], v[22:23], v[14:15], v[6:7] op_sel_hi:[0,1,1]
	v_mov_b32_e32 v10, v3
	v_pk_fma_f32 v[2:3], v[66:67], v[10:11], v[6:7] op_sel_hi:[0,1,1]
	v_mov_b32_e32 v6, v4
	v_mov_b32_e32 v7, v12
	v_pk_fma_f32 v[2:3], v[16:17], v[6:7], v[2:3] op_sel_hi:[0,1,1]
	v_mov_b32_e32 v12, v5
	v_pk_fma_f32 v[62:63], v[64:65], v[12:13], v[2:3] op_sel_hi:[0,1,1]
	ds_read_b32 v2, v53 offset:32828
	v_add_u32_e32 v53, 64, v53
	s_waitcnt lgkmcnt(0)
	v_fmac_f32_e32 v93, v64, v2
	s_andn2_b64 exec, exec, s[0:1]
	s_cbranch_execnz .LBB0_538
	s_or_b64 exec, exec, s[0:1]
	ds_write2st64_b32 v48, v0, v1 offset0:144 offset1:145
	ds_write2st64_b32 v48, v8, v9 offset0:146 offset1:147
	ds_write2st64_b32 v48, v60, v61 offset0:148 offset1:149
	ds_write2st64_b32 v48, v62, v63 offset0:150 offset1:151
	ds_write_b32 v48, v93 offset:38912
	s_waitcnt lgkmcnt(0)
	s_barrier
	s_and_saveexec_b64 s[0:1], s[38:39]
	s_cbranch_execz .LBB0_542
	s_nop 1
	s_mul_i32 s26, s20, 0x6000
	v_readlane_b32 s14, v253, 42
	v_readlane_b32 s15, v253, 43
	s_add_u32 s26, s14, s26
	s_addc_u32 s27, s15, 0
	s_and_b32 s23, 0xffff, s23
	s_lshl_b32 s88, s23, 2
	s_add_u32 s26, s26, s88
	s_addc_u32 s27, s27, 0
	v_lshlrev_b32_e32 v184, 2, v42
	s_mul_i32 s20, s20, 9
	v_lshl_add_u64 v[0:1], s[26:27], 0, v[184:185]
	v_lshl_add_u64 v[2:3], v[50:51], 0, s[88:89]
	s_mov_b64 s[28:29], 0
	v_mov_b32_e32 v4, v91
	v_mov_b32_e32 v5, v40
	s_nop 1

.LBB0_546:
	s_or_saveexec_b64 s[0:1], s[30:31]
	s_mov_b32 s20, 0x3f22f983
	v_mul_f32_e64 v6, |v2|, s20
	v_rndne_f32_e32 v6, v6
	s_xor_b64 exec, exec, s[0:1]
	v_cvt_i32_f32_e32 v1, v6
	s_mov_b32 s4, 0xbfc90fda
	v_fma_f32 v7, v6, s4, |v2|
	v_fmac_f32_e32 v7, 0xb3a22168, v6
	v_fmac_f32_e32 v7, 0xa7c234c4, v6
	s_or_b64 exec, exec, s[0:1]
	v_mul_f32_e32 v8, v7, v7
	v_fmamk_f32 v9, v8, 0xb94c1982, v223
	v_fmaak_f32 v9, v8, v9, 0xbe2aaa9d
	v_mul_f32_e32 v9, v8, v9
	v_fmac_f32_e32 v7, v7, v9
	v_fmamk_f32 v9, v8, 0x37d75334, v224
	v_fmaak_f32 v9, v8, v9, 0x3d2aabf7
	v_fmaak_f32 v9, v8, v9, 0xbf000004
	v_fma_f32 v8, v8, v9, 1.0
	v_and_b32_e32 v9, 1, v1
	v_cmp_eq_u32_e32 vcc, 0, v9
	v_lshlrev_b32_e32 v1, 30, v1
	s_movk_i32 s0, 0x1f8
	v_cndmask_b32_e64 v7, -v7, v8, vcc
	v_bitop3_b32 v1, v1, v7, s53 bitop3:0x6c
	v_cmp_class_f32_e64 vcc, v2, s0
	v_lshl_or_b32 v0, v0, 6, v47
	s_nop 1
	v_cndmask_b32_e32 v7, v236, v1, vcc
	v_ashrrev_i32_e32 v1, 31, v0
	v_readlane_b32 s16, v253, 28
	v_readlane_b32 s17, v253, 29
	s_nop 1
	v_lshl_add_u64 v[0:1], v[0:1], 2, s[16:17]
	s_nop 1
	global_store_dword v[0:1], v7, off
	s_and_saveexec_b64 s[0:1], s[28:29]
	s_xor_b64 s[28:29], exec, s[0:1]
	s_cbranch_execz .LBB0_550
	v_cmp_lt_u32_e64 s[0:1], 63, v5
	s_mov_b32 s4, 0xfe5163ab
	s_nop 0
	v_cndmask_b32_e64 v6, 0, v239, s[0:1]
	v_add_u32_e32 v5, v6, v5
	v_cmp_lt_u32_e64 s[48:49], 31, v5
	s_nop 1
	v_cndmask_b32_e64 v6, 0, v240, s[48:49]
	v_add_u32_e32 v5, v6, v5
	v_cmp_lt_u32_e64 s[50:51], 31, v5
	s_nop 1
	v_cndmask_b32_e64 v6, 0, v240, s[50:51]
	v_add_u32_e32 v18, v6, v5
	v_mad_u64_u32 v[6:7], s[26:27], v4, s4, 0
	v_mov_b32_e32 v184, v7
	s_mov_b32 s4, 0x3c439041
	v_mad_u64_u32 v[8:9], s[26:27], v4, s4, v[184:185]
	v_mov_b32_e32 v184, v9
	s_mov_b32 s4, 0xdb629599
	v_mad_u64_u32 v[10:11], s[26:27], v4, s4, v[184:185]
	v_mov_b32_e32 v184, v11
	s_mov_b32 s4, 0xf534ddc0
	v_mad_u64_u32 v[12:13], s[26:27], v4, s4, v[184:185]
	v_mov_b32_e32 v184, v13
	s_mov_b32 s4, 0xfc2757d1
	v_mad_u64_u32 v[14:15], s[26:27], v4, s4, v[184:185]
	v_mov_b32_e32 v184, v15
	s_mov_b32 s4, 0x4e441529
	v_mad_u64_u32 v[16:17], s[26:27], v4, s4, v[184:185]
	v_mov_b32_e32 v184, v17
	s_mov_b32 s4, 0xa2f9836e
	v_mad_u64_u32 v[4:5], s[26:27], v4, s4, v[184:185]
	v_cndmask_b32_e64 v7, v16, v12, s[0:1]
	v_cndmask_b32_e64 v4, v4, v14, s[0:1]
	v_cndmask_b32_e64 v5, v5, v16, s[0:1]
	v_cndmask_b32_e64 v9, v4, v7, s[48:49]
	v_cndmask_b32_e64 v4, v5, v4, s[48:49]
	v_cndmask_b32_e64 v5, v14, v10, s[0:1]
	v_cndmask_b32_e64 v7, v7, v5, s[48:49]
	v_cndmask_b32_e64 v8, v12, v8, s[0:1]
	v_cndmask_b32_e64 v4, v4, v9, s[50:51]
	v_cndmask_b32_e64 v9, v9, v7, s[50:51]
	v_sub_u32_e32 v11, 32, v18
	v_cndmask_b32_e64 v5, v5, v8, s[48:49]
	v_alignbit_b32 v13, v4, v9, v11
	v_cmp_eq_u32_e64 s[52:53], 0, v18
	v_cndmask_b32_e64 v7, v7, v5, s[50:51]
	v_alignbit_b32 v12, v9, v7, v11
	v_cndmask_b32_e64 v4, v13, v4, s[52:53]
	v_cndmask_b32_e64 v6, v10, v6, s[0:1]
	v_cndmask_b32_e64 v9, v12, v9, s[52:53]
	v_bfe_u32 v14, v4, 29, 1
	v_cndmask_b32_e64 v6, v8, v6, s[48:49]
	v_alignbit_b32 v12, v4, v9, 30
	v_sub_u32_e32 v15, 0, v14
	v_cndmask_b32_e64 v5, v5, v6, s[50:51]
	v_xor_b32_e32 v12, v12, v15
	v_alignbit_b32 v6, v7, v5, v11
	v_cndmask_b32_e64 v6, v6, v7, s[52:53]
	v_ffbh_u32_e32 v8, v12
	v_alignbit_b32 v7, v9, v6, 30
	v_min_u32_e32 v8, 32, v8
	v_alignbit_b32 v5, v6, v5, 30
	v_xor_b32_e32 v7, v7, v15
	v_sub_u32_e32 v9, 31, v8
	v_xor_b32_e32 v5, v5, v15
	v_alignbit_b32 v10, v12, v7, v9
	v_alignbit_b32 v5, v7, v5, v9
	v_alignbit_b32 v6, v10, v5, 9
	v_ffbh_u32_e32 v7, v6
	v_min_u32_e32 v7, 32, v7
	v_lshrrev_b32_e32 v13, 29, v4
	v_not_b32_e32 v9, v7
	v_alignbit_b32 v5, v6, v5, v9
	v_lshlrev_b32_e32 v6, 31, v13
	v_or_b32_e32 v9, 0x33000000, v6
	v_add_lshl_u32 v7, v7, v8, 23
	v_lshrrev_b32_e32 v5, 9, v5
	v_sub_u32_e32 v7, v9, v7
	v_or_b32_e32 v6, 0.5, v6
	v_lshlrev_b32_e32 v8, 23, v8
	v_or_b32_e32 v5, v7, v5
	v_lshrrev_b32_e32 v7, 9, v10
	v_sub_u32_e32 v6, v6, v8
	v_or_b32_e32 v6, v7, v6
	v_mul_f32_e32 v7, 0x3fc90fda, v6
	s_mov_b32 s0, 0x3fc90fda
	v_fma_f32 v8, v6, s0, -v7
	v_fmac_f32_e32 v8, 0x33a22168, v6
	s_movk_i32 s50, 0x8000
	v_fmac_f32_e32 v8, 0x3fc90fda, v5
	v_lshrrev_b32_e32 v4, 30, v4
	s_mov_b32 s51, -1
	s_brev_b32 s53, 1
	s_movk_i32 s52, 0x6000
	v_add_f32_e32 v8, v7, v8
	v_add_u32_e32 v7, v14, v4

.LBB0_586:
	s_or_b64 exec, exec, s[28:29]
	s_nop 1
	v_readlane_b32 s18, v253, 14
	v_readlane_b32 s19, v253, 15
	v_cvt_pk_bf16_f32 v2, v2, v4
	v_cvt_pk_bf16_f32 v3, v5, v6
	v_cvt_pk_bf16_f32 v4, v7, v8
	v_cvt_pk_bf16_f32 v5, v9, v13
	s_nop 1
	s_nop 0
	v_lshl_add_u64 v[0:1], v[0:1], 1, s[18:19]
	s_nop 1
	global_store_dwordx4 v[0:1], v[2:5], off
